# prep work not needed by the first GEMM (W2/W3/W4 + cache conversions, rope table, pads) deferred to the idle second block of each CU during the recurrent phase
# speedup vs baseline: 1.0013x; 1.0013x over previous
_Z14hawk_yoco_mega6Params:
	s_load_dwordx8 s[4:11], s[0:1], 0xc0
	v_and_b32_e32 v144, 0x3ff, v0
	s_waitcnt lgkmcnt(0)
	v_writelane_b32 v254, s4, 0
	s_nop 1
	v_writelane_b32 v254, s5, 1
	v_writelane_b32 v254, s6, 2
	v_writelane_b32 v254, s7, 3
	v_writelane_b32 v254, s8, 4
	v_writelane_b32 v254, s9, 5
	v_writelane_b32 v254, s10, 6
	v_writelane_b32 v254, s11, 7
	s_load_dwordx4 s[88:91], s[0:1], 0xe0
	s_load_dwordx2 s[4:5], s[0:1], 0xf0
	s_load_dword s3, s[0:1], 0xf8
	s_add_u32 s6, s0, 0xf8
	s_addc_u32 s7, s1, 0
	v_cmp_eq_u32_e64 s[8:9], 0, v144
	s_waitcnt lgkmcnt(0)
	v_writelane_b32 v254, s4, 8
	s_nop 1
	v_writelane_b32 v254, s5, 9
	v_writelane_b32 v254, s3, 10
	s_mov_b64 s[4:5], exec
	v_writelane_b32 v254, s8, 11
	s_nop 1
	v_writelane_b32 v254, s9, 12
	s_and_b64 s[8:9], s[4:5], s[8:9]
	s_mov_b64 exec, s[8:9]
	s_cbranch_execz .LBB0_4
	s_mov_b64 s[10:11], src_shared_base
	s_getreg_b32 s3, hwreg(HW_REG_XCC_ID)
	s_and_b32 s3, s3, 7
	s_add_i32 s10, 0, 0x11ff0
	s_cmp_lg_u32 s10, -1
	s_cselect_b32 s10, s10, 0
	s_cselect_b32 s11, s11, 0
	s_mov_b64 s[8:9], exec
	v_mov_b32_e32 v2, s10
	v_mov_b32_e32 v3, s11
	v_mov_b32_e32 v1, s3
	flat_store_dword v[2:3], v1 sc0 sc1
	s_waitcnt vmcnt(0)
	s_getreg_b32 s14, hwreg(HW_REG_HW_ID)
	s_bfe_u32 s14, s14, 0x70008
	s_lshr_b32 s15, s14, 5
	s_and_b32 s14, s14, 31
	s_lshl_b32 s16, s3, 2
	s_add_u32 s15, s15, s16
	s_lshl_b32 s15, s15, 2
	s_lshl_b32 s17, 1, s14
	v_mov_b32_e32 v4, s15
	v_add_u32_e32 v4, 0x1bf9c480, v4
	v_mov_b32_e32 v5, s17
	global_atomic_or v6, v4, v5, s[90:91] sc0
	s_waitcnt vmcnt(0)
	v_lshrrev_b32_e32 v6, s14, v6
	v_and_b32_e32 v6, 1, v6
	v_mov_b32_e32 v7, 0x7fffffff
	v_mov_b32_e32 v8, 0
	v_mov_b32_e32 v5, 1
	v_readfirstlane_b32 s20, v6
	s_nop 1
	s_cmp_eq_u32 s20, 0
	s_cbranch_scc0 .Lsolo_rank1
	v_mov_b32_e32 v4, s16
	v_add_u32_e32 v4, 0x1bf9c420, v4
	global_atomic_add v7, v4, v5, s[90:91] sc0
	s_branch .Lsolo_reg_done
.Lsolo_rank1:
	v_mov_b32_e32 v4, 0x1bf9c448
	global_atomic_add v8, v4, v5, s[90:91] sc0
.Lsolo_reg_done:
	s_waitcnt vmcnt(0)
	v_mov_b32_e32 v4, 0x11ff8
	ds_write_b32 v4, v7
	ds_write_b32 v4, v8 offset:4
	s_waitcnt lgkmcnt(0)
	v_mbcnt_lo_u32_b32 v1, s8, 0
	v_mbcnt_hi_u32_b32 v1, s9, v1
	v_cmp_eq_u32_e32 vcc, 0, v1
	s_and_saveexec_b64 s[10:11], vcc
	s_cbranch_execz .LBB0_3
	s_lshl_b32 s3, s3, 2
	s_add_u32 s12, s90, s3
	s_addc_u32 s13, s91, 0
	s_bcnt1_i32_b64 s3, s[8:9]
	v_mov_b32_e32 v2, 0x1bf9c000
	v_mov_b32_e32 v3, s3
	global_atomic_add v2, v2, v3, s[12:13] offset:1024 sc0

.LBB0_4:
	s_or_b64 exec, exec, s[4:5]
	s_load_dwordx16 s[8:23], s[0:1], 0x0
	s_mov_b32 s39, 0
	s_waitcnt lgkmcnt(0)
	v_writelane_b32 v254, s8, 13
	s_nop 1
	v_writelane_b32 v254, s9, 14
	v_writelane_b32 v254, s10, 15
	v_writelane_b32 v254, s11, 16
	v_writelane_b32 v254, s12, 17
	v_writelane_b32 v254, s13, 18
	v_writelane_b32 v254, s14, 19
	v_writelane_b32 v254, s15, 20
	v_writelane_b32 v254, s16, 21
	v_writelane_b32 v254, s17, 22
	v_writelane_b32 v254, s18, 23
	v_writelane_b32 v254, s19, 24
	v_writelane_b32 v254, s20, 25
	v_writelane_b32 v254, s21, 26
	v_writelane_b32 v254, s22, 27
	v_writelane_b32 v254, s23, 28
	s_load_dwordx16 s[56:71], s[0:1], 0x40
	s_load_dwordx16 s[8:23], s[0:1], 0x80
	s_mov_b64 s[0:1], src_shared_base
	s_add_i32 s0, 0, 0x11ff0
	s_cmp_lg_u32 s0, -1
	s_cselect_b32 s0, s0, 0
	s_cselect_b32 s3, s1, 0
	v_mov_b32_e32 v2, s0
	s_add_i32 s0, 0, 0x11ff4
	s_cmp_lg_u32 s0, -1
	v_mov_b32_e32 v3, s3
	s_cselect_b32 s0, s0, 0
	s_cselect_b32 s1, s1, 0
	s_waitcnt lgkmcnt(0)
	s_barrier
	flat_load_dword v1, v[2:3] sc0 sc1
	s_waitcnt vmcnt(0)
	v_mov_b32_e32 v2, s0
	v_mov_b32_e32 v3, s1
	flat_load_dword v76, v[2:3] sc0 sc1
	s_waitcnt vmcnt(0)
	v_mov_b32_e32 v2, 0x11ff8
	ds_read_b32 v3, v2 offset:4
	ds_read_b32 v2, v2
	s_waitcnt lgkmcnt(0)
	v_readfirstlane_b32 s99, v2
	v_readfirstlane_b32 s100, v3
	v_writelane_b32 v254, s8, 29
	s_waitcnt lgkmcnt(0)
	s_barrier
	v_writelane_b32 v254, s9, 30
	v_writelane_b32 v254, s10, 31
	v_writelane_b32 v254, s11, 32
	v_writelane_b32 v254, s12, 33
	v_writelane_b32 v254, s13, 34
	v_writelane_b32 v254, s14, 35
	v_writelane_b32 v254, s15, 36
	v_writelane_b32 v254, s16, 37
	v_writelane_b32 v254, s17, 38
	v_writelane_b32 v254, s18, 39
	v_writelane_b32 v254, s19, 40
	v_writelane_b32 v254, s20, 41
	v_writelane_b32 v254, s21, 42
	v_writelane_b32 v254, s22, 43
	v_writelane_b32 v254, s23, 44
	s_nop 0
	v_readlane_b32 s8, v254, 8
	v_readlane_b32 s9, v254, 9
	v_writelane_b32 v254, s56, 45
	s_cmp_lt_i32 s8, 1
	s_cselect_b64 s[0:1], -1, 0
	v_writelane_b32 v254, s57, 46
	v_writelane_b32 v254, s58, 47
	v_writelane_b32 v254, s59, 48
	v_writelane_b32 v254, s60, 49
	v_writelane_b32 v254, s61, 50
	v_writelane_b32 v254, s62, 51
	v_writelane_b32 v254, s63, 52
	v_writelane_b32 v254, s64, 53
	v_writelane_b32 v254, s65, 54
	v_writelane_b32 v254, s66, 55
	v_writelane_b32 v254, s67, 56
	s_cmp_gt_i32 s9, 0
	v_writelane_b32 v254, s68, 57
	s_cselect_b64 s[4:5], -1, 0
	v_writelane_b32 v254, s69, 58
	s_and_b64 s[0:1], s[0:1], s[4:5]
	v_writelane_b32 v254, s70, 59
	s_andn2_b64 vcc, exec, s[0:1]
	v_writelane_b32 v254, s71, 60
	s_cbranch_vccnz .LBB0_137
	s_cmpk_lt_i32 s2, 0x2c0
	s_cselect_b64 s[4:5], -1, 0
	s_and_b64 s[0:1], s[4:5], exec
	s_cselect_b32 s0, s2, 0
	s_add_u32 s3, s90, 0x19a88000
	s_addc_u32 s33, s91, 0
	s_add_u32 s8, s90, 0x1bbc8000
	s_addc_u32 s9, s91, 0
	s_add_u32 s10, s90, 0x1b3c8000
	s_addc_u32 s11, s91, 0
	s_add_u32 s12, s90, 0x1ab88000
	s_addc_u32 s13, s91, 0
	s_add_u32 s14, s90, 0x1b108000
	s_addc_u32 s15, s91, 0
	v_readlane_b32 s16, v254, 13
	s_cmpk_lt_i32 s0, 0x2c0
	v_readlane_b32 s28, v254, 25
	v_readlane_b32 s29, v254, 26
	v_readlane_b32 s30, v254, 27
	v_readlane_b32 s31, v254, 28
	v_readlane_b32 s17, v254, 14
	v_readlane_b32 s18, v254, 15
	v_readlane_b32 s19, v254, 16
	v_readlane_b32 s20, v254, 17
	v_readlane_b32 s21, v254, 18
	v_readlane_b32 s22, v254, 19
	v_readlane_b32 s23, v254, 20
	v_readlane_b32 s24, v254, 21
	v_readlane_b32 s25, v254, 22
	v_readlane_b32 s26, v254, 23
	v_readlane_b32 s27, v254, 24
	s_cbranch_scc1 .LBB0_10
	s_cmpk_lt_u32 s0, 0x420
	s_cbranch_scc1 .LBB0_11
	v_mov_b32_e32 v2, 0x620
	v_sub_co_u32_e32 v2, vcc, s0, v2
	v_readlane_b32 s72, v254, 29
	v_readfirstlane_b32 s16, v2
	s_and_b32 s40, s0, 31
	s_and_b64 vcc, exec, vcc
	v_readlane_b32 s73, v254, 30
	v_readlane_b32 s74, v254, 31
	v_readlane_b32 s75, v254, 32
	v_readlane_b32 s78, v254, 35
	v_readlane_b32 s79, v254, 36
	v_readlane_b32 s80, v254, 37
	v_readlane_b32 s81, v254, 38
	v_readlane_b32 s76, v254, 33
	v_readlane_b32 s77, v254, 34
	v_readlane_b32 s82, v254, 39
	v_readlane_b32 s83, v254, 40
	v_readlane_b32 s84, v254, 41
	v_readlane_b32 s85, v254, 42
	v_readlane_b32 s86, v254, 43
	v_readlane_b32 s87, v254, 44
	s_cbranch_vccnz .LBB0_12
	v_mov_b32_e32 v2, 0x820
	v_sub_co_u32_e32 v2, vcc, s0, v2
	s_nop 0
	v_readfirstlane_b32 s1, v2
	s_and_b64 vcc, exec, vcc
	s_cbranch_vccnz .LBB0_13
	v_mov_b32_e32 v2, 0x920
	v_readlane_b32 s16, v254, 0
	v_sub_co_u32_e32 v7, vcc, s0, v2
	s_nop 0
	v_readfirstlane_b32 s16, v7
	v_readlane_b32 s17, v254, 1
	s_lshr_b32 s16, s16, 5
	v_readlane_b32 s18, v254, 2
	s_mul_hi_u32 s17, s16, 0x44000
	s_mul_i32 s16, s16, 0x44000
	v_readlane_b32 s19, v254, 3
	v_readlane_b32 s20, v254, 4
	s_add_u32 s18, s3, s16
	v_lshrrev_b32_e32 v2, 8, v7
	v_mov_b32_e32 v3, 0
	v_readlane_b32 s36, v254, 13
	s_addc_u32 s19, s33, s17
	s_bfe_u32 s20, s0, 0x40001
	s_lshr_b32 s1, s1, 4
	v_lshlrev_b64 v[4:5], 22, v[2:3]
	v_readlane_b32 s46, v254, 23
	v_readlane_b32 s47, v254, 24
	v_lshlrev_b32_e32 v2, 4, v7
	s_and_b64 s[16:17], vcc, exec
	v_readlane_b32 s23, v254, 7
	v_readlane_b32 s37, v254, 14
	v_readlane_b32 s40, v254, 17
	v_lshl_add_u64 v[4:5], s[46:47], 0, v[4:5]
	v_and_b32_e32 v2, 0xe00, v2
	s_cselect_b32 s16, s8, s18
	s_movk_i32 s18, 0x400
	s_cselect_b32 s36, s1, s20
	s_cselect_b32 s1, 15, 1
	v_readlane_b32 s22, v254, 6
	v_mov_b32_e32 v6, s23
	v_lshl_add_u64 v[2:3], v[4:5], 0, v[2:3]
	s_cselect_b32 s17, s9, s19
	s_cselect_b32 s37, s18, 0x440
	s_and_b32 s40, s0, s1
	v_readlane_b32 s21, v254, 5
	v_readlane_b32 s38, v254, 15
	v_readlane_b32 s39, v254, 16
	v_cndmask_b32_e32 v19, v3, v6, vcc
	v_mov_b32_e32 v3, s22
	s_and_b64 s[0:1], vcc, exec
	v_cndmask_b32_e32 v18, v2, v3, vcc
	s_mov_b32 s39, 0
	s_cselect_b32 s38, 0x400, 0
	s_mov_b64 s[18:19], 0x400
	s_mov_b64 s[20:21], 0
	v_readlane_b32 s41, v254, 18
	v_readlane_b32 s42, v254, 19
	v_readlane_b32 s43, v254, 20
	v_readlane_b32 s44, v254, 21
	v_readlane_b32 s45, v254, 22
	v_readlane_b32 s48, v254, 25
	v_readlane_b32 s49, v254, 26
	v_readlane_b32 s50, v254, 27
	v_readlane_b32 s51, v254, 28
	s_branch .LBB0_14

.LBB0_26:
	v_readlane_b32 s0, v254, 10
	s_add_i32 s41, s41, s0
	s_cmpk_gt_i32 s41, 0x2bf
	s_cselect_b64 s[18:19], -1, 0
	s_cmpk_lt_i32 s41, 0x2c0
	s_cselect_b64 s[0:1], -1, 0
	s_and_b64 s[20:21], s[0:1], exec
	s_cselect_b32 s30, s41, 0
	s_cmpk_gt_i32 s30, 0x2bf
	s_waitcnt vmcnt(3)
	ds_write_b128 v40, v[2:5]
	s_waitcnt vmcnt(2)
	ds_write_b128 v40, v[6:9] offset:4352
	s_waitcnt vmcnt(1)
	ds_write_b128 v40, v[10:13] offset:8704
	s_waitcnt vmcnt(0)
	ds_write_b128 v40, v[14:17] offset:13056
	s_waitcnt lgkmcnt(0)
	s_barrier
	s_cbranch_scc0 .LBB0_33
	s_cmpk_gt_u32 s30, 0x41f
	s_cbranch_scc0 .LBB0_34
	s_cmpk_gt_u32 s30, 0x61f
	s_cbranch_scc0 .LBB0_35
	s_cmpk_gt_u32 s30, 0x81f
	s_cbranch_scc0 .LBB0_36
	s_cmpk_gt_u32 s30, 0x91f
	s_cbranch_scc0 .LBB0_38
	s_add_i32 s22, s30, 0xfffff6e0
	s_lshr_b32 s4, s22, 8
	v_readlane_b32 s44, v254, 13
	s_lshr_b32 s24, s22, 5
	s_lshl_b64 s[20:21], s[4:5], 22
	v_readlane_b32 s54, v254, 23
	v_readlane_b32 s55, v254, 24
	s_add_u32 s4, s54, s20
	s_addc_u32 s20, s55, s21
	s_lshl_b32 s21, s22, 4
	s_and_b32 s21, s21, 0xe00
	s_add_u32 s22, s4, s21
	v_readlane_b32 s56, v254, 25
	v_readlane_b32 s57, v254, 26
	v_readlane_b32 s58, v254, 27
	v_readlane_b32 s59, v254, 28
	s_addc_u32 s23, s20, 0
	s_mul_hi_u32 s4, s24, 0x44000
	s_mul_i32 s24, s24, 0x44000
	v_readlane_b32 s56, v254, 45
	s_add_u32 s20, s3, s24
	v_readlane_b32 s45, v254, 14
	v_readlane_b32 s46, v254, 15
	v_readlane_b32 s47, v254, 16
	v_readlane_b32 s48, v254, 17
	v_readlane_b32 s49, v254, 18
	v_readlane_b32 s50, v254, 19
	v_readlane_b32 s51, v254, 20
	v_readlane_b32 s52, v254, 21
	v_readlane_b32 s53, v254, 22
	v_readlane_b32 s57, v254, 46
	v_readlane_b32 s58, v254, 47
	v_readlane_b32 s59, v254, 48
	v_readlane_b32 s60, v254, 49
	v_readlane_b32 s61, v254, 50
	v_readlane_b32 s62, v254, 51
	v_readlane_b32 s63, v254, 52
	v_readlane_b32 s64, v254, 53
	v_readlane_b32 s65, v254, 54
	v_readlane_b32 s66, v254, 55
	v_readlane_b32 s67, v254, 56
	v_readlane_b32 s68, v254, 57
	v_readlane_b32 s69, v254, 58
	v_readlane_b32 s70, v254, 59
	v_readlane_b32 s71, v254, 60
	s_addc_u32 s21, s33, s4
	s_bfe_u32 s4, s30, 0x40001
	s_and_b32 s42, s30, 1
	s_cbranch_execz .LBB0_39
	s_movk_i32 s44, 0x440
	s_mov_b32 s43, 0
	s_branch .LBB0_40

.LBB0_69:
	s_or_b64 exec, exec, s[0:1]
	s_mov_b32 s0, 0x20000
	v_cmp_gt_i32_e32 vcc, s0, v18
	v_ashrrev_i32_e32 v19, 31, v18
	s_and_saveexec_b64 s[0:1], vcc
	s_branch .LBB0_72
	s_waitcnt vmcnt(3)
	v_and_b32_e32 v2, 31, v144
	v_cvt_f32_ubyte0_e32 v2, v2
	v_mul_f32_e32 v3, 0xbed49a78, v2
	s_mov_b32 s3, 0xc2fc0000
	v_mov_b32_e32 v4, 0x42800000
	v_cmp_gt_f32_e32 vcc, s3, v3
	s_mov_b64 s[4:5], 0x1be58000
	s_ashr_i32 s9, s8, 31
	v_cndmask_b32_e32 v3, 0, v4, vcc
	v_fmac_f32_e32 v3, 0xbed49a78, v2
	v_exp_f32_e32 v2, v3
	v_not_b32_e32 v3, 63
	v_cndmask_b32_e32 v3, 0, v3, vcc
	s_mov_b32 s12, 0x6dc9c883
	v_ldexp_f32 v4, v2, v3
	v_lshl_add_u64 v[2:3], v[18:19], 3, s[90:91]
	s_mov_b32 s14, 0x54442d18
	v_lshl_add_u64 v[2:3], v[2:3], 0, s[4:5]
	s_lshl_b64 s[4:5], s[8:9], 3
	s_mov_b64 s[10:11], 0
	s_mov_b32 s13, 0x3fc45f30
	s_mov_b32 s15, 0xc01921fb
	s_mov_b32 s3, 0x1ffff
	v_mov_b32_e32 v5, v18
	s_waitcnt vmcnt(0)

.LBB0_72:
	s_or_b64 exec, exec, s[0:1]
	s_mov_b32 s3, 0x200000
	v_cmp_gt_i32_e32 vcc, s3, v18
	s_and_saveexec_b64 s[10:11], vcc
	s_branch .LBB0_87
	s_add_u32 s12, s90, 0x18988000
	s_addc_u32 s13, s91, 0
	v_readlane_b32 s0, v254, 10
	s_add_i32 s24, s8, s8
	s_ashr_i32 s9, s8, 31
	v_lshl_add_u32 v23, s2, 10, v27
	s_lshl_b32 s18, s0, 12
	s_lshl_b32 s19, s0, 9
	s_lshl_b32 s20, s0, 11
	s_mul_i32 s21, s0, 0x300
	s_mul_i32 s22, s0, 0xc00
	s_lshl_b32 s23, s0, 10
	s_mov_b64 s[14:15], 0
	v_mov_b32_e32 v21, 0
	s_add_i32 s24, s24, s8
	s_mov_b32 s25, 0x1fffff
	v_mov_b32_e32 v24, v18
	s_branch .LBB0_75

.LBB0_87:
	s_or_b64 exec, exec, s[10:11]
	s_waitcnt vmcnt(3)
	v_cvt_f32_u32_e32 v2, s8
	s_mov_b32 s0, 0x30000
	v_cmp_gt_i32_e32 vcc, s0, v18
	v_add_u32_e32 v3, s8, v18
	s_waitcnt vmcnt(2)
	v_rcp_iflag_f32_e32 v8, v2
	s_and_saveexec_b64 s[4:5], vcc
	s_branch .LBB0_102
	v_mul_f32_e32 v5, 0x4f7ffffe, v8
	v_cvt_u32_f32_e32 v5, v5
	v_mov_b32_e32 v4, s8
	v_cmp_gt_i32_e32 vcc, s0, v3
	v_max_i32_e32 v2, 0x30000, v3
	s_mov_b64 s[12:13], -1
	v_addc_co_u32_e64 v4, s[0:1], v18, v4, vcc
	s_sub_i32 s0, 0, s8
	v_sub_u32_e32 v2, v2, v4
	v_mul_lo_u32 v4, s0, v5
	v_mul_hi_u32 v4, v5, v4
	v_add_u32_e32 v4, v5, v4
	v_mul_hi_u32 v4, v2, v4
	v_mul_lo_u32 v5, v4, s8
	v_sub_u32_e32 v2, v2, v5
	v_add_u32_e32 v5, 1, v4
	v_cmp_le_u32_e64 s[0:1], s8, v2
	s_nop 1
	v_cndmask_b32_e64 v4, v4, v5, s[0:1]
	v_subrev_u32_e32 v5, s8, v2
	v_cndmask_b32_e64 v2, v2, v5, s[0:1]
	v_add_u32_e32 v5, 1, v4
	v_cmp_le_u32_e64 s[0:1], s8, v2
	s_nop 1
	v_cndmask_b32_e64 v2, v4, v5, s[0:1]
	v_addc_co_u32_e32 v9, vcc, 1, v2, vcc
	v_cmp_lt_u32_e64 s[0:1], 1, v9
	s_waitcnt vmcnt(1)
	v_and_b32_e32 v10, -2, v9
	v_mov_b32_e32 v4, v18
	s_and_saveexec_b64 s[10:11], s[0:1]
	s_cbranch_execz .LBB0_92
	v_readlane_b32 s3, v254, 10
	v_and_b32_e32 v6, -2, v9
	v_mov_b32_e32 v2, v18
	s_lshl_b32 s3, s3, 9
	s_mov_b32 s9, s3
	s_mov_b64 s[12:13], 0
	s_mov_b32 s14, 0x2aaaaaab
	s_mov_b32 s15, 0x18b90000
	v_mov_b32_e32 v7, 0
	v_mov_b32_e32 v11, v6
	v_mov_b64_e32 v[4:5], v[2:3]
	s_waitcnt vmcnt(0)

.LBB0_137:
	v_mov_b32_e32 v0, 0x1bf9c000
	global_load_dword v2, v0, s[90:91] offset:1024 sc1
	global_load_dword v3, v0, s[90:91] offset:1028 sc1
	global_load_dword v4, v0, s[90:91] offset:1032 sc1
	global_load_dword v5, v0, s[90:91] offset:1036 sc1
	global_load_dword v6, v0, s[90:91] offset:1040 sc1
	s_waitcnt lgkmcnt(0)
	global_load_dword v7, v0, s[90:91] offset:1044 sc1
	global_load_dword v8, v0, s[90:91] offset:1048 sc1
	global_load_dword v9, v0, s[90:91] offset:1052 sc1
	s_cmp_lt_i32 s8, 2
	s_cselect_b64 s[0:1], -1, 0
	s_cmp_gt_i32 s9, 1
	s_cselect_b64 s[2:3], -1, 0
	s_and_b64 s[0:1], s[0:1], s[2:3]
	s_andn2_b64 vcc, exec, s[0:1]
	v_cmp_lt_i32_e64 s[0:1], 0, v1
	s_waitcnt vmcnt(7)
	s_nop 0
	v_cndmask_b32_e64 v0, 0, v2, s[0:1]
	v_cmp_eq_u32_e64 s[0:1], 0, v1
	s_nop 1
	v_cndmask_b32_e64 v10, 0, v2, s[0:1]
	v_cmp_lt_i32_e64 s[0:1], 1, v1
	s_waitcnt vmcnt(6)
	s_nop 0
	v_cndmask_b32_e64 v11, 0, v3, s[0:1]
	v_cmp_lt_i32_e64 s[0:1], 0, v3
	s_nop 1
	v_cndmask_b32_e64 v12, 0, 1, s[0:1]
	v_cmp_lt_i32_e64 s[0:1], 2, v1
	s_waitcnt vmcnt(5)
	s_nop 0
	v_cndmask_b32_e64 v13, 0, v4, s[0:1]
	v_cmp_lt_i32_e64 s[0:1], 0, v4
	v_add3_u32 v0, v11, v0, v13
	s_nop 0
	v_cndmask_b32_e64 v14, 0, 1, s[0:1]
	v_cmp_lt_i32_e64 s[0:1], 3, v1
	s_waitcnt vmcnt(4)
	s_nop 0
	v_cndmask_b32_e64 v15, 0, v5, s[0:1]
	v_cmp_lt_i32_e64 s[0:1], 4, v1
	s_waitcnt vmcnt(3)
	s_nop 0
	v_cndmask_b32_e64 v16, 0, v6, s[0:1]
	v_cmp_lt_i32_e64 s[0:1], 0, v6
	v_add3_u32 v0, v15, v0, v16
	s_nop 0
	v_cndmask_b32_e64 v17, 0, 1, s[0:1]
	v_cmp_lt_i32_e64 s[0:1], 5, v1
	s_waitcnt vmcnt(2)
	s_nop 0
	v_cndmask_b32_e64 v18, 0, v7, s[0:1]
	v_cmp_lt_i32_e64 s[0:1], 6, v1
	s_waitcnt vmcnt(1)
	s_nop 0
	v_cndmask_b32_e64 v19, 0, v8, s[0:1]
	v_cmp_lt_i32_e64 s[0:1], 0, v8
	v_add3_u32 v0, v18, v0, v19
	s_nop 0
	v_cndmask_b32_e64 v20, 0, 1, s[0:1]
	v_cmp_lt_i32_e64 s[0:1], 7, v1
	s_waitcnt vmcnt(0)
	s_nop 0
	v_cndmask_b32_e64 v21, 0, v9, s[0:1]
	v_cmp_eq_u32_e64 s[0:1], 1, v1
	v_add3_u32 v200, v21, v0, v76
	v_lshl_or_b32 v197, v1, 9, v200
	v_cndmask_b32_e64 v3, v10, v3, s[0:1]
	v_cmp_lt_i32_e64 s[0:1], 0, v2
	v_bfe_u32 v199, v200, 6, 3
	v_and_b32_e32 v198, 63, v200
	v_addc_co_u32_e64 v2, s[0:1], 0, v12, s[0:1]
	v_cmp_eq_u32_e64 s[0:1], 2, v1
	s_nop 1
	v_cndmask_b32_e64 v3, v3, v4, s[0:1]
	v_cmp_lt_i32_e64 s[0:1], 0, v5
	s_nop 1
	v_addc_co_u32_e64 v2, s[0:1], v2, v14, s[0:1]
	v_cmp_eq_u32_e64 s[0:1], 3, v1
	s_nop 1
	v_cndmask_b32_e64 v3, v3, v5, s[0:1]
	v_cmp_lt_i32_e64 s[0:1], 0, v7
	s_nop 1
	v_addc_co_u32_e64 v2, s[0:1], v2, v17, s[0:1]
	v_cmp_eq_u32_e64 s[0:1], 4, v1
	s_nop 1
	v_cndmask_b32_e64 v3, v3, v6, s[0:1]
	v_cmp_lt_i32_e64 s[0:1], 0, v9
	s_nop 1
	v_addc_co_u32_e64 v2, s[0:1], v2, v20, s[0:1]
	v_cmp_eq_u32_e64 s[0:1], 5, v1
	v_lshlrev_b32_e32 v2, 22, v2
	s_nop 0
	v_cndmask_b32_e64 v0, v3, v7, s[0:1]
	v_cmp_eq_u32_e64 s[0:1], 6, v1
	s_nop 1
	v_cndmask_b32_e64 v0, v0, v8, s[0:1]
	v_cmp_eq_u32_e64 s[0:1], 7, v1
	s_nop 1
	v_cndmask_b32_e64 v0, v0, v9, s[0:1]
	v_lshlrev_b32_e32 v0, 12, v0
	v_or3_b32 v196, v0, v2, v197
	v_mov_b32_e32 v40, 0x1bf9c000
	v_lshl_add_u32 v40, v1, 2, v40
	v_mov_b32_e32 v41, 0x1bf9c000
	global_load_dword v41, v41, s[90:91] offset:1096 sc1
	global_load_dword v40, v40, s[90:91] offset:1056 sc1
	s_waitcnt vmcnt(0)
	v_readfirstlane_b32 s98, v40
	v_readfirstlane_b32 s101, v41
	s_cbranch_vccnz .LBB0_299
	v_readlane_b32 s0, v254, 10
	s_lshr_b32 s0, s0, 6
	s_sub_i32 s1, 0, s0
	v_cvt_f32_u32_e32 v0, s0
	v_and_b32_e32 v145, 63, v200
	v_rcp_iflag_f32_e32 v1, v0
	v_bfe_u32 v0, v200, 6, 3
	v_cmp_eq_u32_e32 vcc, 0, v0
	v_mul_f32_e32 v1, 0x4f7ffffe, v1
	v_cvt_u32_f32_e32 v1, v1
	v_cndmask_b32_e64 v2, 0, 22, vcc
	v_readfirstlane_b32 s2, v1
	s_mul_i32 s1, s1, s2
	s_mul_hi_u32 s1, s2, s1
	s_add_i32 s2, s2, s1
	s_lshr_b32 s1, s2, 25
	s_mul_i32 s2, s1, s0
	s_sub_i32 s2, 0x80, s2
	s_add_i32 s3, s1, 1
	s_sub_i32 s4, s2, s0
	s_cmp_ge_u32 s2, s0
	s_cselect_b32 s1, s3, s1
	s_cselect_b32 s2, s4, s2
	s_add_i32 s3, s1, 1
	s_cmp_ge_u32 s2, s0
	s_cselect_b32 s2, s3, s1
	v_mad_u64_u32 v[140:141], s[0:1], s2, 22, v[2:3]
	v_cmp_lt_u32_e64 s[0:1], v145, v140
	s_and_saveexec_b64 s[6:7], s[0:1]
	s_cbranch_execz .LBB0_289
	s_add_u32 s8, s90, 0x1bf58000
	v_mul_u32_u24_e32 v201, s2, v0
	v_lshlrev_b32_e32 v0, 4, v144
	s_addc_u32 s9, s91, 0
	v_lshrrev_b32_e32 v1, 5, v144
	v_and_b32_e32 v8, 0x3c0, v0
	v_bitop3_b32 v9, v0, 48, v144 bitop3:0x48
	v_bfe_u32 v0, v144, 2, 2
	s_add_u32 s12, s90, 0x1ab88000
	v_bitop3_b32 v1, v1, v0, 1 bitop3:0x6c
	s_addc_u32 s13, s91, 0
	s_lshl_b32 s54, s2, 3
	v_lshlrev_b32_e32 v202, 4, v1
	v_lshlrev_b32_e32 v1, 3, v144
	v_and_b32_e32 v2, 56, v1
	v_cvt_f32_u32_e32 v1, s54
	v_lshrrev_b32_e32 v5, 6, v144
	v_lshlrev_b32_e32 v7, 10, v5
	v_and_b32_e32 v141, 31, v144
	v_rcp_iflag_f32_e32 v1, v1
	v_bfe_u32 v3, v144, 5, 1
	v_lshrrev_b32_e32 v4, 7, v144
	v_add_u32_e32 v204, 0, v7
	v_mul_f32_e32 v1, 0x4f7ffffe, v1
	v_cvt_u32_f32_e32 v1, v1
	s_movk_i32 s0, 0x1e00
	v_bitop3_b32 v0, v3, v0, 2 bitop3:0x36
	v_lshlrev_b32_e32 v205, 5, v4
	v_lshlrev_b32_e32 v212, 11, v4
	v_mad_u32_u24 v4, v5, s0, v204
	v_mul_u32_u24_e32 v5, 0x110, v141
	v_lshlrev_b32_e32 v3, 4, v3
	s_sub_i32 s0, 0, s54
	v_bfe_u32 v6, v144, 6, 1
	v_bfe_u32 v206, v144, 3, 3
	v_add3_u32 v213, v4, v5, v3
	v_mul_lo_u32 v5, s0, v1
	v_or3_b32 v142, v8, v9, v7
	v_lshlrev_b32_e32 v203, 4, v0
	v_lshlrev_b32_e32 v0, 6, v6
	v_mov_b32_e32 v147, 0
	v_lshlrev_b32_e32 v210, 12, v6
	v_lshlrev_b32_e32 v211, 6, v141
	v_lshl_add_u32 v3, v2, 2, v4
	v_mul_u32_u24_e32 v4, 0x110, v206
	v_mul_hi_u32 v5, v1, v5
	v_or3_b32 v150, v7, v8, v9
	s_mov_b64 s[10:11], 0x1ab88000
	v_or_b32_e32 v207, 8, v206
	v_or_b32_e32 v208, 16, v206
	v_or_b32_e32 v209, 24, v206
	v_mov_b32_e32 v143, v147
	v_add_u32_e32 v148, 0x1000, v142
	v_mov_b32_e32 v149, v147
	v_add3_u32 v214, 0, v210, v211
	v_add3_u32 v215, 0, v212, v211
	v_add_u32_e32 v216, v1, v5
	v_or_b32_e32 v152, 0xb0000, v150
	v_mov_b32_e32 v153, v147
	v_or_b32_e32 v154, 0x808000, v150
	v_mov_b32_e32 v155, v147
	v_mov_b32_e32 v151, v147
	v_or_b32_e32 v156, 0x58000, v150
	v_mov_b32_e32 v157, v147
	v_or_b32_e32 v158, 0x404000, v150
	v_mov_b32_e32 v159, v147
	v_or_b32_e32 v160, 0x84000, v150
	v_mov_b32_e32 v161, v147
	v_add_u32_e32 v162, 0x606000, v150
	v_mov_b32_e32 v163, v147
	s_mov_b64 s[14:15], 0
	s_mov_b64 s[16:17], 0x202000
	s_mov_b64 s[18:19], 0x2c000
	s_mov_b64 s[20:21], 0x1000
	s_mov_b64 s[22:23], 0x1ab89000
	s_mov_b64 s[24:25], 0x606000
	s_mov_b64 s[26:27], 0x1ac0d000
	s_mov_b64 s[28:29], 0x84000
	s_mov_b64 s[30:31], 0x2000
	s_mov_b64 s[34:35], 0x3000
	s_mov_b64 s[36:37], 0x204000
	s_mov_b64 s[38:39], 0x205000
	s_mov_b64 s[40:41], 0x404000
	s_mov_b64 s[42:43], 0x405000
	s_mov_b64 s[44:45], 0x406000
	s_mov_b64 s[46:47], 0x407000
	s_mov_b64 s[48:49], 0x1abe0000
	s_mov_b64 s[50:51], 0x1abe1000
	s_mov_b64 s[60:61], 0x58000
	v_lshlrev_b32_e32 v164, 1, v0
	v_lshlrev_b32_e32 v166, 1, v2
	s_movk_i32 s55, 0xb00
	v_mov_b32_e32 v217, 0x4040000
	v_mov_b32_e32 v218, 0x9898000
	v_add_u32_e32 v219, v3, v4
	s_branch .LBB0_142
.LBB0_140:
	s_or_b64 exec, exec, s[2:3]
	v_mov_b32_e32 v33, v0
	v_mov_b32_e32 v35, v2
	v_mov_b32_e32 v0, v17
	v_mov_b32_e32 v2, v19
	ds_write_b128 v213, v[0:3] offset:128
	v_mov_b32_e32 v0, v20
	v_mov_b32_e32 v1, v4
	v_mov_b32_e32 v2, v22
	v_mov_b32_e32 v3, v6
	ds_write_b128 v213, v[0:3] offset:32
	v_mov_b32_e32 v0, v24
	v_mov_b32_e32 v1, v8
	v_mov_b32_e32 v2, v26
	v_mov_b32_e32 v3, v10
	v_mov_b32_e32 v32, v16
	v_mov_b32_e32 v34, v18
	v_mov_b32_e32 v4, v21
	v_mov_b32_e32 v6, v23
	ds_write_b128 v213, v[0:3] offset:64
	v_mov_b32_e32 v8, v25
	v_mov_b32_e32 v10, v27
	v_mov_b32_e32 v0, v28
	v_mov_b32_e32 v1, v12
	v_mov_b32_e32 v2, v30
	v_mov_b32_e32 v3, v14
	v_mov_b32_e32 v12, v29
	v_mov_b32_e32 v14, v31
	ds_write_b128 v213, v[32:35]
	ds_write_b128 v213, v[4:7] offset:160
	ds_write_b128 v213, v[8:11] offset:192
	ds_write_b128 v213, v[0:3] offset:96
	ds_write_b128 v213, v[12:15] offset:224
	s_waitcnt lgkmcnt(0)
	s_barrier
	ds_read_b128 v[0:3], v219
	ds_read_b128 v[4:7], v219 offset:16
	s_waitcnt lgkmcnt(1)
	v_cvt_pk_bf16_f32 v0, v0, v1
	v_cvt_pk_bf16_f32 v1, v2, v3
	s_waitcnt lgkmcnt(0)
	v_cvt_pk_bf16_f32 v2, v4, v5
	v_cvt_pk_bf16_f32 v3, v6, v7
	ds_read_b128 v[4:7], v219 offset:2176
	ds_read_b128 v[8:11], v219 offset:2192
	v_add_u32_e32 v14, 0xc0, v106
	v_or_b32_e32 v12, v14, v206
	v_mad_i64_i32 v[12:13], s[2:3], v12, s55, v[48:49]
	global_store_dwordx4 v[12:13], v[0:3], off
	v_or_b32_e32 v12, v14, v207
	v_mad_i64_i32 v[12:13], s[2:3], v12, s55, v[48:49]
	s_waitcnt lgkmcnt(1)
	v_cvt_pk_bf16_f32 v0, v4, v5
	v_cvt_pk_bf16_f32 v1, v6, v7
	s_waitcnt lgkmcnt(0)
	v_cvt_pk_bf16_f32 v2, v8, v9
	v_cvt_pk_bf16_f32 v3, v10, v11
	ds_read_b128 v[4:7], v219 offset:4352
	ds_read_b128 v[8:11], v219 offset:4368
	global_store_dwordx4 v[12:13], v[0:3], off
	v_or_b32_e32 v12, v14, v208
	v_mad_i64_i32 v[12:13], s[2:3], v12, s55, v[48:49]
	s_waitcnt lgkmcnt(1)
	v_cvt_pk_bf16_f32 v0, v4, v5
	v_cvt_pk_bf16_f32 v1, v6, v7
	s_waitcnt lgkmcnt(0)
	v_cvt_pk_bf16_f32 v2, v8, v9
	v_cvt_pk_bf16_f32 v3, v10, v11
	ds_read_b128 v[4:7], v219 offset:6528
	ds_read_b128 v[8:11], v219 offset:6544
	global_store_dwordx4 v[12:13], v[0:3], off
	s_waitcnt lgkmcnt(1)
	s_nop 0
	v_cvt_pk_bf16_f32 v0, v4, v5
	v_or_b32_e32 v4, v14, v209
	v_mad_i64_i32 v[4:5], s[2:3], v4, s55, v[48:49]
	v_cvt_pk_bf16_f32 v1, v6, v7
	s_waitcnt lgkmcnt(0)
	v_cvt_pk_bf16_f32 v2, v8, v9
	v_cvt_pk_bf16_f32 v3, v10, v11
	global_store_dwordx4 v[4:5], v[0:3], off
	s_barrier

.LBB0_152:
	s_or_saveexec_b64 s[0:1], s[0:1]
	v_mov_b32_e32 v176, 0
	v_mov_b32_e32 v94, 0
	v_mov_b32_e32 v182, 0
	v_mov_b32_e32 v92, 0
	v_mov_b32_e32 v184, 0
	v_mov_b32_e32 v90, 0
	v_mov_b32_e32 v186, 0
	v_mov_b32_e32 v88, 0
	v_mov_b32_e32 v188, 0
	v_mov_b32_e32 v86, 0
	v_mov_b32_e32 v190, 0
	v_mov_b32_e32 v84, 0
	v_mov_b32_e32 v192, 0
	v_mov_b32_e32 v82, 0
	v_mov_b32_e32 v194, 0
	v_mov_b32_e32 v80, 0
	v_mov_b32_e32 v128, 0
	v_mov_b32_e32 v46, 0
	v_mov_b32_e32 v130, 0
	v_mov_b32_e32 v44, 0
	v_mov_b32_e32 v132, 0
	v_mov_b32_e32 v42, 0
	v_mov_b32_e32 v134, 0
	v_mov_b32_e32 v40, 0
	v_mov_b32_e32 v136, 0
	v_mov_b32_e32 v38, 0
	v_mov_b32_e32 v138, 0
	v_mov_b32_e32 v36, 0
	v_mov_b32_e32 v172, 0
	v_mov_b32_e32 v34, 0
	v_mov_b32_e32 v174, 0
	v_mov_b32_e32 v32, 0
	v_mov_b32_e32 v177, 0
	v_mov_b32_e32 v95, 0
	v_mov_b32_e32 v183, 0
	v_mov_b32_e32 v93, 0
	v_mov_b32_e32 v185, 0
	v_mov_b32_e32 v91, 0
	v_mov_b32_e32 v187, 0
	v_mov_b32_e32 v89, 0
	v_mov_b32_e32 v189, 0
	v_mov_b32_e32 v87, 0
	v_mov_b32_e32 v191, 0
	v_mov_b32_e32 v85, 0
	v_mov_b32_e32 v193, 0
	v_mov_b32_e32 v83, 0
	v_mov_b32_e32 v195, 0
	v_mov_b32_e32 v81, 0
	v_mov_b32_e32 v129, 0
	v_mov_b32_e32 v47, 0
	v_mov_b32_e32 v131, 0
	v_mov_b32_e32 v45, 0
	v_mov_b32_e32 v133, 0
	v_mov_b32_e32 v43, 0
	v_mov_b32_e32 v135, 0
	v_mov_b32_e32 v41, 0
	v_mov_b32_e32 v137, 0
	v_mov_b32_e32 v39, 0
	v_mov_b32_e32 v139, 0
	v_mov_b32_e32 v37, 0
	v_mov_b32_e32 v173, 0
	v_mov_b32_e32 v35, 0
	v_mov_b32_e32 v175, 0
	v_mov_b32_e32 v33, 0
	s_xor_b64 exec, exec, s[0:1]
	s_cbranch_execz .LBB0_156
	v_add_u32_e32 v2, 0x2000, v204
	v_lshl_add_u64 v[0:1], v[100:101], 0, s[30:31]
	v_readfirstlane_b32 s4, v2
	v_add_u32_e32 v2, 0x3000, v204
	s_mov_b32 m0, s4
	v_readfirstlane_b32 s4, v2
	global_load_lds_dwordx4 v[0:1], off
	v_lshl_add_u64 v[0:1], v[100:101], 0, s[34:35]
	s_mov_b32 m0, s4
	v_readfirstlane_b32 s4, v119
	global_load_lds_dwordx4 v[0:1], off
	s_mov_b32 m0, s4
	v_readfirstlane_b32 s4, v118
	global_load_lds_dwordx4 v[112:113], off
	s_mov_b32 m0, s4
	v_readfirstlane_b32 s4, v117
	global_load_lds_dwordx4 v[110:111], off
	s_mov_b32 m0, s4
	v_readfirstlane_b32 s4, v116
	v_add_u32_e32 v2, 0x8000, v204
	global_load_lds_dwordx4 v[108:109], off
	s_mov_b32 m0, s4
	v_readfirstlane_b32 s4, v2
	v_add_u32_e32 v2, 0x9000, v204
	global_load_lds_dwordx4 v[106:107], off
	v_lshl_add_u64 v[0:1], v[100:101], 0, s[36:37]
	s_mov_b32 m0, s4
	v_readfirstlane_b32 s4, v2
	global_load_lds_dwordx4 v[0:1], off
	v_lshl_add_u64 v[0:1], v[100:101], 0, s[38:39]
	s_mov_b32 m0, s4
	v_readfirstlane_b32 s4, v115
	global_load_lds_dwordx4 v[0:1], off
	s_mov_b32 m0, s4
	v_readfirstlane_b32 s4, v114
	global_load_lds_dwordx4 v[104:105], off
	s_mov_b32 m0, s4
	v_lshl_add_u64 v[174:175], v[162:163], 0, v[96:97]
	global_load_lds_dwordx4 v[102:103], off
	v_mov_b32_e32 v96, 0
	v_lshl_add_u64 v[172:173], v[160:161], 0, v[98:99]
	s_mov_b32 s5, 0
	s_mov_b32 s33, 2
	s_mov_b32 s4, 30
	v_mov_b32_e32 v97, v96
	v_mov_b32_e32 v98, v96
	v_mov_b32_e32 v99, v96
	v_mov_b32_e32 v100, v96
	v_mov_b32_e32 v101, v96
	v_mov_b32_e32 v102, v96
	v_mov_b32_e32 v103, v96
	v_mov_b32_e32 v104, v96
	v_mov_b32_e32 v105, v96
	v_mov_b32_e32 v106, v96
	v_mov_b32_e32 v107, v96
	v_mov_b32_e32 v108, v96
	v_mov_b32_e32 v109, v96
	v_mov_b32_e32 v110, v96
	v_mov_b32_e32 v111, v96
	v_mov_b32_e32 v112, v96
	v_mov_b32_e32 v113, v96
	v_mov_b32_e32 v114, v96
	v_mov_b32_e32 v115, v96
	v_mov_b32_e32 v116, v96
	v_mov_b32_e32 v117, v96
	v_mov_b32_e32 v118, v96
	v_mov_b32_e32 v119, v96
	v_mov_b32_e32 v120, v96
	v_mov_b32_e32 v121, v96
	v_mov_b32_e32 v122, v96
	v_mov_b32_e32 v123, v96
	v_mov_b32_e32 v124, v96
	v_mov_b32_e32 v125, v96
	v_mov_b32_e32 v126, v96
	v_mov_b32_e32 v127, v96
	v_mov_b32_e32 v0, v96
	v_mov_b32_e32 v1, v96
	v_mov_b32_e32 v2, v96
	v_mov_b32_e32 v3, v96
	v_mov_b32_e32 v4, v96
	v_mov_b32_e32 v5, v96
	v_mov_b32_e32 v6, v96
	v_mov_b32_e32 v7, v96
	v_mov_b32_e32 v8, v96
	v_mov_b32_e32 v9, v96
	v_mov_b32_e32 v10, v96
	v_mov_b32_e32 v11, v96
	v_mov_b32_e32 v12, v96
	v_mov_b32_e32 v13, v96
	v_mov_b32_e32 v14, v96
	v_mov_b32_e32 v15, v96
	v_mov_b32_e32 v48, v96
	v_mov_b32_e32 v49, v96
	v_mov_b32_e32 v50, v96
	v_mov_b32_e32 v51, v96
	v_mov_b32_e32 v52, v96
	v_mov_b32_e32 v53, v96
	v_mov_b32_e32 v54, v96
	v_mov_b32_e32 v55, v96
	v_mov_b32_e32 v56, v96
	v_mov_b32_e32 v57, v96
	v_mov_b32_e32 v58, v96
	v_mov_b32_e32 v59, v96
	v_mov_b32_e32 v60, v96
	v_mov_b32_e32 v61, v96
	v_mov_b32_e32 v62, v96
	v_mov_b32_e32 v63, v96
	v_mov_b32_e32 v32, v96
	v_mov_b32_e32 v33, v96
	v_mov_b32_e32 v34, v96
	v_mov_b32_e32 v35, v96
	v_mov_b32_e32 v36, v96
	v_mov_b32_e32 v37, v96
	v_mov_b32_e32 v38, v96
	v_mov_b32_e32 v39, v96
	v_mov_b32_e32 v40, v96
	v_mov_b32_e32 v41, v96
	v_mov_b32_e32 v42, v96
	v_mov_b32_e32 v43, v96
	v_mov_b32_e32 v44, v96
	v_mov_b32_e32 v45, v96
	v_mov_b32_e32 v46, v96
	v_mov_b32_e32 v47, v96
	v_mov_b32_e32 v80, v96
	v_mov_b32_e32 v81, v96
	v_mov_b32_e32 v82, v96
	v_mov_b32_e32 v83, v96
	v_mov_b32_e32 v84, v96
	v_mov_b32_e32 v85, v96
	v_mov_b32_e32 v86, v96
	v_mov_b32_e32 v87, v96
	v_mov_b32_e32 v88, v96
	v_mov_b32_e32 v89, v96
	v_mov_b32_e32 v90, v96
	v_mov_b32_e32 v91, v96
	v_mov_b32_e32 v92, v96
	v_mov_b32_e32 v93, v96
	v_mov_b32_e32 v94, v96
	v_mov_b32_e32 v95, v96
	v_mov_b32_e32 v16, v96
	v_mov_b32_e32 v17, v96
	v_mov_b32_e32 v18, v96
	v_mov_b32_e32 v19, v96
	v_mov_b32_e32 v20, v96
	v_mov_b32_e32 v21, v96
	v_mov_b32_e32 v22, v96
	v_mov_b32_e32 v23, v96
	v_mov_b32_e32 v24, v96
	v_mov_b32_e32 v25, v96
	v_mov_b32_e32 v26, v96
	v_mov_b32_e32 v27, v96
	v_mov_b32_e32 v28, v96
	v_mov_b32_e32 v29, v96
	v_mov_b32_e32 v30, v96
	v_mov_b32_e32 v31, v96
	v_mov_b32_e32 v64, v96
	v_mov_b32_e32 v65, v96
	v_mov_b32_e32 v66, v96
	v_mov_b32_e32 v67, v96
	v_mov_b32_e32 v68, v96
	v_mov_b32_e32 v69, v96
	v_mov_b32_e32 v70, v96
	v_mov_b32_e32 v71, v96
	v_mov_b32_e32 v72, v96
	v_mov_b32_e32 v73, v96
	v_mov_b32_e32 v74, v96
	v_mov_b32_e32 v75, v96
	v_mov_b32_e32 v76, v96
	v_mov_b32_e32 v77, v96
	v_mov_b32_e32 v78, v96
	v_mov_b32_e32 v79, v96
.LBB0_154:
	s_mul_i32 s52, s33, 0x6000
	v_add_u32_e32 v132, s52, v204
	v_lshl_add_u64 v[128:129], s[90:91], 0, v[180:181]
	v_readfirstlane_b32 s52, v132
	v_add_u32_e32 v133, 0x1000, v132
	s_waitcnt vmcnt(6)
	v_lshl_add_u64 v[130:131], v[128:129], 0, s[40:41]
	s_mov_b32 m0, s52
	v_readfirstlane_b32 s52, v133
	v_add_u32_e32 v133, 0x2000, v132
	s_waitcnt lgkmcnt(0)
	s_barrier
	global_load_lds_dwordx4 v[130:131], off
	v_lshl_add_u64 v[130:131], v[128:129], 0, s[42:43]
	s_mov_b32 m0, s52
	v_readfirstlane_b32 s52, v133
	global_load_lds_dwordx4 v[130:131], off
	v_lshl_add_u64 v[130:131], v[128:129], 0, s[44:45]
	s_mov_b32 m0, s52
	v_lshl_add_u64 v[128:129], v[128:129], 0, s[46:47]
	global_load_lds_dwordx4 v[130:131], off
	v_add_u32_e32 v130, 0x3000, v132
	v_add_u32_e32 v133, 0x4000, v132
	v_readfirstlane_b32 s52, v130
	s_mov_b32 m0, s52
	v_readfirstlane_b32 s52, v133
	global_load_lds_dwordx4 v[128:129], off
	v_lshl_add_u64 v[128:129], s[90:91], 0, v[178:179]
	v_lshl_add_u64 v[130:131], v[128:129], 0, s[48:49]
	s_mov_b32 m0, s52
	v_lshl_add_u64 v[128:129], v[128:129], 0, s[50:51]
	global_load_lds_dwordx4 v[130:131], off
	v_add_u32_e32 v130, 0x5000, v132
	v_lshl_add_u64 v[178:179], v[178:179], 0, s[60:61]
	v_readfirstlane_b32 s52, v130
	s_mov_b32 m0, s52
	s_mul_i32 s52, s5, 0x6000
	s_add_i32 s52, s52, 0
	v_add3_u32 v132, s52, v210, v211
	global_load_lds_dwordx4 v[128:129], off
	v_add_u32_e32 v136, v132, v202
	ds_read_b128 v[128:131], v136 offset:16384
	v_add_u32_e32 v146, v132, v203
	ds_read_b128 v[132:135], v146 offset:16384
	ds_read_b128 v[136:139], v136 offset:18432
	ds_read_b128 v[182:185], v146 offset:18432
	v_add3_u32 v146, s52, v212, v211
	v_add_u32_e32 v165, v146, v202
	ds_read_b128 v[186:189], v165
	v_add_u32_e32 v146, v146, v203
	ds_read_b128 v[190:193], v146
	ds_read_b128 v[220:223], v165 offset:4096
	ds_read_b128 v[224:227], v146 offset:4096
	ds_read_b128 v[228:231], v165 offset:8192
	ds_read_b128 v[232:235], v146 offset:8192
	ds_read_b128 v[236:239], v165 offset:12288
	ds_read_b128 v[240:243], v146 offset:12288
	s_waitcnt lgkmcnt(0)
	v_mfma_f32_32x32x16_bf16 v[64:79], v[128:131], v[186:189], v[64:79]
	s_add_i32 s52, s5, 1
	s_cmp_lg_u32 s5, 2
	s_cselect_b32 s5, s52, 0
	s_add_i32 s52, s33, 1
	s_cmp_lg_u32 s33, 2
	s_cselect_b32 s33, s52, 0
	s_mul_i32 s52, s33, 0x6000
	v_mfma_f32_32x32x16_bf16 v[16:31], v[128:131], v[220:223], v[16:31]
	s_waitcnt vmcnt(6)
	s_waitcnt lgkmcnt(0)
	s_barrier
	v_lshl_add_u64 v[180:181], v[180:181], 0, s[40:41]
	v_mfma_f32_32x32x16_bf16 v[80:95], v[128:131], v[228:231], v[80:95]
	v_mfma_f32_32x32x16_bf16 v[32:47], v[128:131], v[236:239], v[32:47]
	v_lshl_add_u64 v[128:129], s[90:91], 0, v[174:175]
	v_lshl_add_u64 v[130:131], v[128:129], 0, s[20:21]
	v_lshl_add_u64 v[174:175], v[174:175], 0, s[40:41]
	v_mfma_f32_32x32x16_bf16 v[64:79], v[132:135], v[190:193], v[64:79]
	v_mfma_f32_32x32x16_bf16 v[16:31], v[132:135], v[224:227], v[16:31]
	v_mfma_f32_32x32x16_bf16 v[80:95], v[132:135], v[232:235], v[80:95]
	v_mfma_f32_32x32x16_bf16 v[32:47], v[132:135], v[240:243], v[32:47]
	v_add_u32_e32 v132, s52, v204
	v_add_u32_e32 v133, 0x1000, v132
	v_readfirstlane_b32 s52, v132
	s_mov_b32 m0, s52
	v_readfirstlane_b32 s52, v133
	v_add_u32_e32 v133, 0x2000, v132
	global_load_lds_dwordx4 v[128:129], off
	s_mov_b32 m0, s52
	v_readfirstlane_b32 s52, v133
	global_load_lds_dwordx4 v[130:131], off
	v_lshl_add_u64 v[130:131], v[128:129], 0, s[30:31]
	s_mov_b32 m0, s52
	v_lshl_add_u64 v[128:129], v[128:129], 0, s[34:35]
	global_load_lds_dwordx4 v[130:131], off
	v_add_u32_e32 v130, 0x3000, v132
	v_add_u32_e32 v133, 0x4000, v132
	v_readfirstlane_b32 s52, v130
	s_mov_b32 m0, s52
	v_readfirstlane_b32 s52, v133
	global_load_lds_dwordx4 v[128:129], off
	v_lshl_add_u64 v[128:129], s[90:91], 0, v[172:173]
	v_lshl_add_u64 v[130:131], v[128:129], 0, s[10:11]
	s_mov_b32 m0, s52
	v_lshl_add_u64 v[128:129], v[128:129], 0, s[22:23]
	global_load_lds_dwordx4 v[130:131], off
	v_add_u32_e32 v130, 0x5000, v132
	v_mfma_f32_32x32x16_bf16 v[48:63], v[136:139], v[186:189], v[48:63]
	v_readfirstlane_b32 s52, v130
	s_mov_b32 m0, s52
	s_mul_i32 s52, s5, 0x6000
	global_load_lds_dwordx4 v[128:129], off
	s_add_i32 s52, s52, 0
	v_add3_u32 v128, s52, v210, v211
	v_mfma_f32_32x32x16_bf16 v[0:15], v[136:139], v[220:223], v[0:15]
	v_add_u32_e32 v132, v128, v202
	v_add3_u32 v146, s52, v212, v211
	v_add_u32_e32 v133, v128, v203
	v_add_u32_e32 v165, v146, v202
	v_add_u32_e32 v146, v146, v203
	s_add_i32 s52, s5, 1
	s_cmp_lg_u32 s5, 2
	v_mfma_f32_32x32x16_bf16 v[112:127], v[136:139], v[228:231], v[112:127]
	s_cselect_b32 s5, s52, 0
	s_add_i32 s52, s33, 1
	s_cmp_lg_u32 s33, 2
	s_cselect_b32 s33, s52, 0
	s_add_i32 s4, s4, -2
	v_lshl_add_u64 v[172:173], v[172:173], 0, s[60:61]
	s_cmp_eq_u32 s4, 0
	v_mfma_f32_32x32x16_bf16 v[96:111], v[136:139], v[236:239], v[96:111]
	v_mfma_f32_32x32x16_bf16 v[48:63], v[182:185], v[190:193], v[48:63]
	v_mfma_f32_32x32x16_bf16 v[0:15], v[182:185], v[224:227], v[0:15]
	v_mfma_f32_32x32x16_bf16 v[112:127], v[182:185], v[232:235], v[112:127]
	v_mfma_f32_32x32x16_bf16 v[96:111], v[182:185], v[240:243], v[96:111]
	ds_read_b128 v[182:185], v132 offset:16384
	ds_read_b128 v[128:131], v133 offset:16384
	ds_read_b128 v[136:139], v132 offset:18432
	ds_read_b128 v[132:135], v133 offset:18432
	ds_read_b128 v[186:189], v165
	ds_read_b128 v[190:193], v146
	ds_read_b128 v[220:223], v165 offset:4096
	ds_read_b128 v[224:227], v146 offset:4096
	ds_read_b128 v[228:231], v165 offset:8192
	ds_read_b128 v[232:235], v146 offset:8192
	ds_read_b128 v[236:239], v165 offset:12288
	ds_read_b128 v[240:243], v146 offset:12288
	s_waitcnt lgkmcnt(0)
	v_mfma_f32_32x32x16_bf16 v[64:79], v[182:185], v[186:189], v[64:79]
	v_mfma_f32_32x32x16_bf16 v[48:63], v[136:139], v[186:189], v[48:63]
	v_mfma_f32_32x32x16_bf16 v[16:31], v[182:185], v[220:223], v[16:31]
	v_mfma_f32_32x32x16_bf16 v[0:15], v[136:139], v[220:223], v[0:15]
	v_mfma_f32_32x32x16_bf16 v[80:95], v[182:185], v[228:231], v[80:95]
	v_mfma_f32_32x32x16_bf16 v[112:127], v[136:139], v[228:231], v[112:127]
	v_mfma_f32_32x32x16_bf16 v[32:47], v[182:185], v[236:239], v[32:47]
	v_mfma_f32_32x32x16_bf16 v[96:111], v[136:139], v[236:239], v[96:111]
	v_mfma_f32_32x32x16_bf16 v[64:79], v[128:131], v[190:193], v[64:79]
	v_mfma_f32_32x32x16_bf16 v[48:63], v[132:135], v[190:193], v[48:63]
	v_mfma_f32_32x32x16_bf16 v[16:31], v[128:131], v[224:227], v[16:31]
	v_mfma_f32_32x32x16_bf16 v[0:15], v[132:135], v[224:227], v[0:15]
	v_mfma_f32_32x32x16_bf16 v[80:95], v[128:131], v[232:235], v[80:95]
	v_mfma_f32_32x32x16_bf16 v[112:127], v[132:135], v[232:235], v[112:127]
	v_mfma_f32_32x32x16_bf16 v[32:47], v[128:131], v[240:243], v[32:47]
	v_mfma_f32_32x32x16_bf16 v[96:111], v[132:135], v[240:243], v[96:111]
	s_cbranch_scc0 .LBB0_154
	s_mul_i32 s4, s5, 0x6000
	s_add_i32 s4, s4, 0
	v_add3_u32 v132, s4, v210, v211
	s_waitcnt vmcnt(6)
	v_add_u32_e32 v136, v132, v202
	s_waitcnt lgkmcnt(0)
	s_barrier
	ds_read_b128 v[128:131], v136 offset:16384
	v_add_u32_e32 v146, v132, v203
	ds_read_b128 v[132:135], v146 offset:16384
	ds_read_b128 v[136:139], v136 offset:18432
	ds_read_b128 v[172:175], v146 offset:18432
	v_add3_u32 v146, s4, v212, v211
	v_add_u32_e32 v165, v146, v202
	v_add_u32_e32 v146, v146, v203
	ds_read_b128 v[176:179], v165
	ds_read_b128 v[180:183], v146
	ds_read_b128 v[184:187], v165 offset:4096
	ds_read_b128 v[188:191], v146 offset:4096
	ds_read_b128 v[192:195], v165 offset:8192
	ds_read_b128 v[220:223], v146 offset:8192
	ds_read_b128 v[224:227], v165 offset:12288
	ds_read_b128 v[228:231], v146 offset:12288
	s_waitcnt lgkmcnt(0)
	v_mfma_f32_32x32x16_bf16 v[80:95], v[128:131], v[192:195], v[80:95]
	s_waitcnt vmcnt(0)
	s_waitcnt lgkmcnt(0)
	s_barrier
	v_add_u32_e32 v146, v214, v203
	v_add_u32_e32 v165, v215, v203
	v_mfma_f32_32x32x16_bf16 v[112:127], v[136:139], v[192:195], v[112:127]
	v_mfma_f32_32x32x16_bf16 v[32:47], v[128:131], v[224:227], v[32:47]
	v_mfma_f32_32x32x16_bf16 v[96:111], v[136:139], v[224:227], v[96:111]
	v_mfma_f32_32x32x16_bf16 v[64:79], v[128:131], v[176:179], v[64:79]
	v_mfma_f32_32x32x16_bf16 v[48:63], v[136:139], v[176:179], v[48:63]
	v_mfma_f32_32x32x16_bf16 v[16:31], v[128:131], v[184:187], v[16:31]
	v_mfma_f32_32x32x16_bf16 v[0:15], v[136:139], v[184:187], v[0:15]
	v_add_u32_e32 v136, v214, v202
	ds_read_b128 v[128:131], v136 offset:40960
	v_mfma_f32_32x32x16_bf16 v[80:95], v[132:135], v[220:223], v[80:95]
	v_mfma_f32_32x32x16_bf16 v[112:127], v[172:175], v[220:223], v[112:127]
	v_mfma_f32_32x32x16_bf16 v[32:47], v[132:135], v[228:231], v[32:47]
	v_mfma_f32_32x32x16_bf16 v[96:111], v[172:175], v[228:231], v[96:111]
	v_mfma_f32_32x32x16_bf16 v[64:79], v[132:135], v[180:183], v[64:79]
	v_mfma_f32_32x32x16_bf16 v[48:63], v[172:175], v[180:183], v[48:63]
	v_mfma_f32_32x32x16_bf16 v[16:31], v[132:135], v[188:191], v[16:31]
	v_mfma_f32_32x32x16_bf16 v[0:15], v[172:175], v[188:191], v[0:15]
	ds_read_b128 v[132:135], v146 offset:40960
	ds_read_b128 v[136:139], v136 offset:43008
	ds_read_b128 v[172:175], v146 offset:43008
	v_add_u32_e32 v146, v215, v202
	ds_read_b128 v[176:179], v146 offset:24576
	ds_read_b128 v[180:183], v165 offset:24576
	ds_read_b128 v[184:187], v146 offset:28672
	ds_read_b128 v[188:191], v165 offset:28672
	ds_read_b128 v[192:195], v146 offset:32768
	ds_read_b128 v[220:223], v165 offset:32768
	ds_read_b128 v[224:227], v146 offset:36864
	ds_read_b128 v[228:231], v165 offset:36864
	s_waitcnt lgkmcnt(0)
	v_mfma_f32_32x32x16_bf16 v[80:95], v[128:131], v[192:195], v[80:95]
	v_mfma_f32_32x32x16_bf16 v[112:127], v[136:139], v[192:195], v[112:127]
	v_mfma_f32_32x32x16_bf16 v[32:47], v[128:131], v[224:227], v[32:47]
	v_mfma_f32_32x32x16_bf16 v[96:111], v[136:139], v[224:227], v[96:111]
	v_mfma_f32_32x32x16_bf16 v[64:79], v[128:131], v[176:179], v[64:79]
	v_mfma_f32_32x32x16_bf16 v[48:63], v[136:139], v[176:179], v[48:63]
	v_mfma_f32_32x32x16_bf16 v[16:31], v[128:131], v[184:187], v[16:31]
	v_mfma_f32_32x32x16_bf16 v[0:15], v[136:139], v[184:187], v[0:15]
	v_mfma_f32_32x32x16_bf16 v[80:95], v[132:135], v[220:223], v[80:95]
	v_mfma_f32_32x32x16_bf16 v[112:127], v[172:175], v[220:223], v[112:127]
	s_nop 10
	v_mov_b32_e32 v176, v95
	v_mov_b32_e32 v184, v91
	v_mov_b32_e32 v186, v89
	v_mov_b32_e32 v192, v83
	v_mov_b32_e32 v194, v81
	v_mov_b32_e32 v177, v127
	v_mfma_f32_32x32x16_bf16 v[32:47], v[132:135], v[228:231], v[32:47]
	v_mov_b32_e32 v95, v126
	v_mov_b32_e32 v185, v123
	v_mov_b32_e32 v91, v122
	v_mov_b32_e32 v187, v121
	v_mov_b32_e32 v89, v120
	v_mov_b32_e32 v193, v115
	v_mov_b32_e32 v83, v114
	v_mfma_f32_32x32x16_bf16 v[96:111], v[172:175], v[228:231], v[96:111]
	s_nop 3
	v_mov_b32_e32 v128, v47
	v_mov_b32_e32 v130, v45
	v_mov_b32_e32 v136, v39
	v_mov_b32_e32 v138, v37
	v_mov_b32_e32 v195, v113
	v_mov_b32_e32 v81, v112
	s_nop 1
	v_mov_b32_e32 v129, v111
	v_mfma_f32_32x32x16_bf16 v[64:79], v[132:135], v[180:183], v[64:79]
	v_mov_b32_e32 v47, v110
	v_mov_b32_e32 v131, v109
	v_mov_b32_e32 v45, v108
	v_mov_b32_e32 v137, v103
	v_mov_b32_e32 v39, v102
	v_mov_b32_e32 v139, v101
	v_mov_b32_e32 v37, v100
	v_mfma_f32_32x32x16_bf16 v[48:63], v[172:175], v[180:183], v[48:63]
	v_mov_b32_e32 v182, v93
	v_mov_b32_e32 v183, v125
	v_mov_b32_e32 v93, v124
	v_mfma_f32_32x32x16_bf16 v[16:31], v[132:135], v[188:191], v[16:31]
	v_mov_b32_e32 v132, v43
	v_mov_b32_e32 v134, v41
	v_mov_b32_e32 v133, v107
	v_mov_b32_e32 v43, v106
	v_mov_b32_e32 v135, v105
	v_mov_b32_e32 v41, v104
	v_mfma_f32_32x32x16_bf16 v[0:15], v[172:175], v[188:191], v[0:15]
	v_mov_b32_e32 v188, v87
	v_mov_b32_e32 v190, v85
	v_mov_b32_e32 v172, v35
	v_mov_b32_e32 v174, v33
	v_mov_b32_e32 v189, v119
	v_mov_b32_e32 v87, v118
	v_mov_b32_e32 v191, v117
	v_mov_b32_e32 v85, v116
	v_mov_b32_e32 v173, v99
	v_mov_b32_e32 v35, v98
	v_mov_b32_e32 v175, v97
	v_mov_b32_e32 v33, v96

.LBB0_192:
	s_or_b64 exec, exec, s[0:1]
	v_mov_b32_e32 v109, v48
	v_mov_b32_e32 v111, v50
	v_mov_b32_e32 v48, v103
	v_mov_b32_e32 v50, v65
	v_lshlrev_b32_e32 v97, 7, v168
	ds_write_b128 v213, v[48:51] offset:128
	v_mov_b32_e32 v48, v66
	v_mov_b32_e32 v49, v52
	v_mov_b32_e32 v50, v68
	v_mov_b32_e32 v51, v54
	v_add_u32_e32 v99, 0xfffffa80, v97
	ds_write_b128 v213, v[48:51] offset:32
	v_mov_b32_e32 v48, v70
	v_mov_b32_e32 v49, v56
	v_mov_b32_e32 v50, v72
	v_mov_b32_e32 v51, v58
	v_cndmask_b32_e64 v146, v217, v218, s[4:5]
	v_cndmask_b32_e64 v104, v97, v99, s[4:5]
	v_mov_b32_e32 v108, v102
	v_mov_b32_e32 v110, v64
	v_mov_b32_e32 v52, v67
	v_mov_b32_e32 v54, v69
	ds_write_b128 v213, v[48:51] offset:64
	v_mov_b32_e32 v56, v71
	v_mov_b32_e32 v58, v73
	v_mov_b32_e32 v48, v74
	v_mov_b32_e32 v49, v60
	v_mov_b32_e32 v50, v76
	v_mov_b32_e32 v51, v62
	v_mov_b32_e32 v60, v75
	v_mov_b32_e32 v62, v77
	v_lshl_add_u64 v[78:79], s[90:91], 0, v[146:147]
	v_ashrrev_i32_e32 v105, 31, v104
	ds_write_b128 v213, v[108:111]
	ds_write_b128 v213, v[52:55] offset:160
	ds_write_b128 v213, v[56:59] offset:192
	ds_write_b128 v213, v[48:51] offset:96
	ds_write_b128 v213, v[60:63] offset:224
	s_waitcnt lgkmcnt(0)
	s_barrier
	ds_read_b128 v[50:53], v219
	ds_read_b128 v[54:57], v219 offset:16
	v_lshl_add_u64 v[78:79], v[104:105], 1, v[78:79]
	v_mov_b32_e32 v165, v147
	s_waitcnt lgkmcnt(1)
	v_cvt_pk_bf16_f32 v50, v50, v51
	v_cvt_pk_bf16_f32 v51, v52, v53
	s_waitcnt lgkmcnt(0)
	v_cvt_pk_bf16_f32 v52, v54, v55
	v_cvt_pk_bf16_f32 v53, v56, v57
	ds_read_b128 v[54:57], v219 offset:2176
	ds_read_b128 v[58:61], v219 offset:2192
	v_lshl_add_u64 v[48:49], v[78:79], 0, v[164:165]
	v_mov_b32_e32 v167, v147
	v_lshl_add_u64 v[48:49], v[48:49], 0, v[166:167]
	v_or_b32_e32 v62, v106, v206
	v_mad_i64_i32 v[62:63], s[0:1], v62, s55, v[48:49]
	global_store_dwordx4 v[62:63], v[50:53], off
	v_or_b32_e32 v62, v106, v207
	v_mad_i64_i32 v[62:63], s[0:1], v62, s55, v[48:49]
	s_waitcnt lgkmcnt(1)
	v_cvt_pk_bf16_f32 v50, v54, v55
	v_cvt_pk_bf16_f32 v51, v56, v57
	s_waitcnt lgkmcnt(0)
	v_cvt_pk_bf16_f32 v52, v58, v59
	v_cvt_pk_bf16_f32 v53, v60, v61
	ds_read_b128 v[54:57], v219 offset:4352
	ds_read_b128 v[58:61], v219 offset:4368
	global_store_dwordx4 v[62:63], v[50:53], off
	v_or_b32_e32 v62, v106, v208
	v_mad_i64_i32 v[62:63], s[0:1], v62, s55, v[48:49]
	s_waitcnt lgkmcnt(1)
	v_cvt_pk_bf16_f32 v50, v54, v55
	v_cvt_pk_bf16_f32 v51, v56, v57
	s_waitcnt lgkmcnt(0)
	v_cvt_pk_bf16_f32 v52, v58, v59
	v_cvt_pk_bf16_f32 v53, v60, v61
	ds_read_b128 v[54:57], v219 offset:6528
	ds_read_b128 v[58:61], v219 offset:6544
	global_store_dwordx4 v[62:63], v[50:53], off
	s_waitcnt lgkmcnt(1)
	s_nop 0
	v_cvt_pk_bf16_f32 v50, v54, v55
	v_or_b32_e32 v54, v106, v209
	v_cvt_pk_bf16_f32 v51, v56, v57
	v_mad_i64_i32 v[54:55], s[0:1], v54, s55, v[48:49]
	s_waitcnt lgkmcnt(0)
	v_cvt_pk_bf16_f32 v52, v58, v59
	v_cvt_pk_bf16_f32 v53, v60, v61
	global_store_dwordx4 v[54:55], v[50:53], off
	s_barrier
	s_nop 0
	v_mov_b32_e32 v50, v16
	v_mov_b32_e32 v51, v0
	s_waitcnt vmcnt(4)
	v_pk_mul_f32 v[50:51], v[50:51], v[100:101] op_sel_hi:[1,0]
	s_and_saveexec_b64 s[0:1], s[4:5]
	s_cbranch_execz .LBB0_194
	v_mul_f32_e32 v0, 0xbfb8aa3b, v50
	v_mul_f32_e32 v16, 0xbfb8aa3b, v51
	v_exp_f32_e32 v0, v0
	v_exp_f32_e32 v16, v16
	v_add_f32_e32 v0, 1.0, v0
	v_add_f32_e32 v16, 1.0, v16
	v_rcp_f32_e32 v52, v0
	v_rcp_f32_e32 v53, v16
	s_nop 0
	v_pk_mul_f32 v[50:51], v[50:51], v[52:53]

.LBB0_224:
	s_or_b64 exec, exec, s[0:1]
	v_mov_b32_e32 v53, v0
	v_mov_b32_e32 v55, v2
	v_mov_b32_e32 v0, v51
	v_mov_b32_e32 v2, v17
	ds_write_b128 v213, v[0:3] offset:128
	v_mov_b32_e32 v0, v18
	v_mov_b32_e32 v1, v4
	v_mov_b32_e32 v2, v20
	v_mov_b32_e32 v3, v6
	ds_write_b128 v213, v[0:3] offset:32
	v_mov_b32_e32 v0, v22
	v_mov_b32_e32 v1, v8
	v_mov_b32_e32 v2, v24
	v_mov_b32_e32 v3, v10
	v_mov_b32_e32 v52, v50
	v_mov_b32_e32 v54, v16
	v_mov_b32_e32 v4, v19
	v_mov_b32_e32 v6, v21
	ds_write_b128 v213, v[0:3] offset:64
	v_mov_b32_e32 v8, v23
	v_mov_b32_e32 v10, v25
	v_mov_b32_e32 v0, v26
	v_mov_b32_e32 v1, v12
	v_mov_b32_e32 v2, v28
	v_mov_b32_e32 v3, v14
	v_mov_b32_e32 v12, v27
	v_mov_b32_e32 v14, v29
	ds_write_b128 v213, v[52:55]
	ds_write_b128 v213, v[4:7] offset:160
	ds_write_b128 v213, v[8:11] offset:192
	ds_write_b128 v213, v[0:3] offset:96
	ds_write_b128 v213, v[12:15] offset:224
	s_waitcnt lgkmcnt(0)
	s_barrier
	ds_read_b128 v[0:3], v219
	ds_read_b128 v[4:7], v219 offset:16
	s_waitcnt lgkmcnt(1)
	v_cvt_pk_bf16_f32 v0, v0, v1
	v_cvt_pk_bf16_f32 v1, v2, v3
	s_waitcnt lgkmcnt(0)
	v_cvt_pk_bf16_f32 v2, v4, v5
	v_cvt_pk_bf16_f32 v3, v6, v7
	ds_read_b128 v[4:7], v219 offset:2176
	ds_read_b128 v[8:11], v219 offset:2192
	v_add_u32_e32 v14, 64, v106
	v_or_b32_e32 v12, v14, v206
	v_mad_i64_i32 v[12:13], s[0:1], v12, s55, v[48:49]
	global_store_dwordx4 v[12:13], v[0:3], off
	v_or_b32_e32 v12, v14, v207
	v_mad_i64_i32 v[12:13], s[0:1], v12, s55, v[48:49]
	s_waitcnt lgkmcnt(1)
	v_cvt_pk_bf16_f32 v0, v4, v5
	v_cvt_pk_bf16_f32 v1, v6, v7
	s_waitcnt lgkmcnt(0)
	v_cvt_pk_bf16_f32 v2, v8, v9
	v_cvt_pk_bf16_f32 v3, v10, v11
	ds_read_b128 v[4:7], v219 offset:4352
	ds_read_b128 v[8:11], v219 offset:4368
	global_store_dwordx4 v[12:13], v[0:3], off
	v_or_b32_e32 v12, v14, v208
	v_mad_i64_i32 v[12:13], s[0:1], v12, s55, v[48:49]
	s_waitcnt lgkmcnt(1)
	v_cvt_pk_bf16_f32 v0, v4, v5
	v_cvt_pk_bf16_f32 v1, v6, v7
	s_waitcnt lgkmcnt(0)
	v_cvt_pk_bf16_f32 v2, v8, v9
	v_cvt_pk_bf16_f32 v3, v10, v11
	ds_read_b128 v[4:7], v219 offset:6528
	ds_read_b128 v[8:11], v219 offset:6544
	global_store_dwordx4 v[12:13], v[0:3], off
	s_waitcnt lgkmcnt(1)
	s_nop 0
	v_cvt_pk_bf16_f32 v0, v4, v5
	v_or_b32_e32 v4, v14, v209
	v_mad_i64_i32 v[4:5], s[0:1], v4, s55, v[48:49]
	v_cvt_pk_bf16_f32 v1, v6, v7
	s_waitcnt lgkmcnt(0)
	v_cvt_pk_bf16_f32 v2, v8, v9
	v_cvt_pk_bf16_f32 v3, v10, v11
	global_store_dwordx4 v[4:5], v[0:3], off
	s_barrier
	s_and_saveexec_b64 s[0:1], s[2:3]
	s_cbranch_execz .LBB0_141
	v_pk_mul_f32 v[16:17], v[80:81], v[98:99] op_sel_hi:[1,0]
	s_and_saveexec_b64 s[2:3], s[4:5]
	s_cbranch_execz .LBB0_227
	v_mul_f32_e32 v0, 0xbfb8aa3b, v16
	v_mul_f32_e32 v1, 0xbfb8aa3b, v17
	v_exp_f32_e32 v0, v0
	v_exp_f32_e32 v1, v1
	v_add_f32_e32 v0, 1.0, v0
	v_add_f32_e32 v1, 1.0, v1
	v_rcp_f32_e32 v0, v0
	v_rcp_f32_e32 v1, v1
	s_nop 0
	v_pk_mul_f32 v[16:17], v[16:17], v[0:1]

.LBB0_243:
	s_or_b64 exec, exec, s[2:3]
	v_mov_b32_e32 v51, v0
	v_mov_b32_e32 v53, v2
	v_mov_b32_e32 v0, v17
	v_mov_b32_e32 v2, v19
	ds_write_b128 v213, v[0:3] offset:128
	v_mov_b32_e32 v0, v20
	v_mov_b32_e32 v1, v4
	v_mov_b32_e32 v2, v22
	v_mov_b32_e32 v3, v6
	ds_write_b128 v213, v[0:3] offset:32
	v_mov_b32_e32 v0, v24
	v_mov_b32_e32 v1, v8
	v_mov_b32_e32 v2, v26
	v_mov_b32_e32 v3, v10
	v_mov_b32_e32 v50, v16
	v_mov_b32_e32 v52, v18
	v_mov_b32_e32 v4, v21
	v_mov_b32_e32 v6, v23
	ds_write_b128 v213, v[0:3] offset:64
	v_mov_b32_e32 v8, v25
	v_mov_b32_e32 v10, v27
	v_mov_b32_e32 v0, v28
	v_mov_b32_e32 v1, v12
	v_mov_b32_e32 v2, v30
	v_mov_b32_e32 v3, v14
	v_mov_b32_e32 v12, v29
	v_mov_b32_e32 v14, v31
	ds_write_b128 v213, v[50:53]
	ds_write_b128 v213, v[4:7] offset:160
	ds_write_b128 v213, v[8:11] offset:192
	ds_write_b128 v213, v[0:3] offset:96
	ds_write_b128 v213, v[12:15] offset:224
	s_waitcnt lgkmcnt(0)
	s_barrier
	ds_read_b128 v[0:3], v219
	ds_read_b128 v[4:7], v219 offset:16
	s_waitcnt lgkmcnt(1)
	v_cvt_pk_bf16_f32 v0, v0, v1
	v_cvt_pk_bf16_f32 v1, v2, v3
	s_waitcnt lgkmcnt(0)
	v_cvt_pk_bf16_f32 v2, v4, v5
	v_cvt_pk_bf16_f32 v3, v6, v7
	ds_read_b128 v[4:7], v219 offset:2176
	ds_read_b128 v[8:11], v219 offset:2192
	v_add_u32_e32 v14, 0x80, v106
	v_or_b32_e32 v12, v14, v206
	v_mad_i64_i32 v[12:13], s[2:3], v12, s55, v[48:49]
	global_store_dwordx4 v[12:13], v[0:3], off
	v_or_b32_e32 v12, v14, v207
	v_mad_i64_i32 v[12:13], s[2:3], v12, s55, v[48:49]
	s_waitcnt lgkmcnt(1)
	v_cvt_pk_bf16_f32 v0, v4, v5
	v_cvt_pk_bf16_f32 v1, v6, v7
	s_waitcnt lgkmcnt(0)
	v_cvt_pk_bf16_f32 v2, v8, v9
	v_cvt_pk_bf16_f32 v3, v10, v11
	ds_read_b128 v[4:7], v219 offset:4352
	ds_read_b128 v[8:11], v219 offset:4368
	global_store_dwordx4 v[12:13], v[0:3], off
	v_or_b32_e32 v12, v14, v208
	v_mad_i64_i32 v[12:13], s[2:3], v12, s55, v[48:49]
	s_waitcnt lgkmcnt(1)
	v_cvt_pk_bf16_f32 v0, v4, v5
	v_cvt_pk_bf16_f32 v1, v6, v7
	s_waitcnt lgkmcnt(0)
	v_cvt_pk_bf16_f32 v2, v8, v9
	v_cvt_pk_bf16_f32 v3, v10, v11
	ds_read_b128 v[4:7], v219 offset:6528
	ds_read_b128 v[8:11], v219 offset:6544
	global_store_dwordx4 v[12:13], v[0:3], off
	v_pk_mul_f32 v[16:17], v[32:33], v[96:97] op_sel_hi:[1,0]
	s_waitcnt lgkmcnt(1)
	v_cvt_pk_bf16_f32 v0, v4, v5
	v_or_b32_e32 v4, v14, v209
	v_mad_i64_i32 v[4:5], s[2:3], v4, s55, v[48:49]
	v_cvt_pk_bf16_f32 v1, v6, v7
	s_waitcnt lgkmcnt(0)
	v_cvt_pk_bf16_f32 v2, v8, v9
	v_cvt_pk_bf16_f32 v3, v10, v11
	global_store_dwordx4 v[4:5], v[0:3], off
	s_barrier
	s_and_saveexec_b64 s[2:3], s[4:5]
	s_cbranch_execz .LBB0_245
	v_mul_f32_e32 v0, 0xbfb8aa3b, v16
	v_mul_f32_e32 v1, 0xbfb8aa3b, v17
	v_exp_f32_e32 v0, v0
	v_exp_f32_e32 v1, v1
	v_add_f32_e32 v0, 1.0, v0
	v_add_f32_e32 v1, 1.0, v1
	v_rcp_f32_e32 v0, v0
	v_rcp_f32_e32 v1, v1
	s_nop 0
	v_pk_mul_f32 v[16:17], v[16:17], v[0:1]

.LBB0_299:
	s_cmp_lt_i32 s8, 3
	s_cselect_b64 s[0:1], -1, 0
	s_cmp_gt_i32 s9, 2
	s_cselect_b64 s[2:3], -1, 0
	s_and_b64 s[0:1], s[0:1], s[2:3]
	s_andn2_b64 vcc, exec, s[0:1]
	s_cbranch_vccnz .LBB0_520
	s_cmp_lg_u32 s99, 0x7fffffff
	s_cbranch_scc1 .Lprep2_skip
	s_add_i32 s2, s100, 0x2c0
	s_mov_b32 s39, 0
	s_cmpk_lt_i32 s2, 0x1120
	s_cselect_b64 s[4:5], -1, 0
	s_and_b64 s[0:1], s[4:5], exec
	s_cselect_b32 s0, s2, 0
	s_add_u32 s3, s90, 0x19a88000
	s_addc_u32 s33, s91, 0
	s_add_u32 s8, s90, 0x1bbc8000
	s_addc_u32 s9, s91, 0
	s_add_u32 s10, s90, 0x1b3c8000
	s_addc_u32 s11, s91, 0
	s_add_u32 s12, s90, 0x1ab88000
	s_addc_u32 s13, s91, 0
	s_add_u32 s14, s90, 0x1b108000
	s_addc_u32 s15, s91, 0
	v_readlane_b32 s16, v254, 13
	s_cmpk_lt_i32 s0, 0x2c0
	v_readlane_b32 s28, v254, 25
	v_readlane_b32 s29, v254, 26
	v_readlane_b32 s30, v254, 27
	v_readlane_b32 s31, v254, 28
	v_readlane_b32 s17, v254, 14
	v_readlane_b32 s18, v254, 15
	v_readlane_b32 s19, v254, 16
	v_readlane_b32 s20, v254, 17
	v_readlane_b32 s21, v254, 18
	v_readlane_b32 s22, v254, 19
	v_readlane_b32 s23, v254, 20
	v_readlane_b32 s24, v254, 21
	v_readlane_b32 s25, v254, 22
	v_readlane_b32 s26, v254, 23
	v_readlane_b32 s27, v254, 24
	s_cbranch_scc1 .Lq_10
	s_cmpk_lt_u32 s0, 0x420
	s_cbranch_scc1 .Lq_11
	v_mov_b32_e32 v2, 0x620
	v_sub_co_u32_e32 v2, vcc, s0, v2
	v_readlane_b32 s72, v254, 29
	v_readfirstlane_b32 s16, v2
	s_and_b32 s40, s0, 31
	s_and_b64 vcc, exec, vcc
	v_readlane_b32 s73, v254, 30
	v_readlane_b32 s74, v254, 31
	v_readlane_b32 s75, v254, 32
	v_readlane_b32 s78, v254, 35
	v_readlane_b32 s79, v254, 36
	v_readlane_b32 s80, v254, 37
	v_readlane_b32 s81, v254, 38
	v_readlane_b32 s76, v254, 33
	v_readlane_b32 s77, v254, 34
	v_readlane_b32 s82, v254, 39
	v_readlane_b32 s83, v254, 40
	v_readlane_b32 s84, v254, 41
	v_readlane_b32 s85, v254, 42
	v_readlane_b32 s86, v254, 43
	v_readlane_b32 s87, v254, 44
	s_cbranch_vccnz .Lq_12
	v_mov_b32_e32 v2, 0x820
	v_sub_co_u32_e32 v2, vcc, s0, v2
	s_nop 0
	v_readfirstlane_b32 s1, v2
	s_and_b64 vcc, exec, vcc
	s_cbranch_vccnz .Lq_13
	v_mov_b32_e32 v2, 0x920
	v_readlane_b32 s16, v254, 0
	v_sub_co_u32_e32 v7, vcc, s0, v2
	s_nop 0
	v_readfirstlane_b32 s16, v7
	v_readlane_b32 s17, v254, 1
	s_lshr_b32 s16, s16, 5
	v_readlane_b32 s18, v254, 2
	s_mul_hi_u32 s17, s16, 0x44000
	s_mul_i32 s16, s16, 0x44000
	v_readlane_b32 s19, v254, 3
	v_readlane_b32 s20, v254, 4
	s_add_u32 s18, s3, s16
	v_lshrrev_b32_e32 v2, 8, v7
	v_mov_b32_e32 v3, 0
	v_readlane_b32 s36, v254, 13
	s_addc_u32 s19, s33, s17
	s_bfe_u32 s20, s0, 0x40001
	s_lshr_b32 s1, s1, 4
	v_lshlrev_b64 v[4:5], 22, v[2:3]
	v_readlane_b32 s46, v254, 23
	v_readlane_b32 s47, v254, 24
	v_lshlrev_b32_e32 v2, 4, v7
	s_and_b64 s[16:17], vcc, exec
	v_readlane_b32 s23, v254, 7
	v_readlane_b32 s37, v254, 14
	v_readlane_b32 s40, v254, 17
	v_lshl_add_u64 v[4:5], s[46:47], 0, v[4:5]
	v_and_b32_e32 v2, 0xe00, v2
	s_cselect_b32 s16, s8, s18
	s_movk_i32 s18, 0x400
	s_cselect_b32 s36, s1, s20
	s_cselect_b32 s1, 15, 1
	v_readlane_b32 s22, v254, 6
	v_mov_b32_e32 v6, s23
	v_lshl_add_u64 v[2:3], v[4:5], 0, v[2:3]
	s_cselect_b32 s17, s9, s19
	s_cselect_b32 s37, s18, 0x440
	s_and_b32 s40, s0, s1
	v_readlane_b32 s21, v254, 5
	v_readlane_b32 s38, v254, 15
	v_readlane_b32 s39, v254, 16
	v_cndmask_b32_e32 v19, v3, v6, vcc
	v_mov_b32_e32 v3, s22
	s_and_b64 s[0:1], vcc, exec
	v_cndmask_b32_e32 v18, v2, v3, vcc
	s_mov_b32 s39, 0
	s_cselect_b32 s38, 0x400, 0
	s_mov_b64 s[18:19], 0x400
	s_mov_b64 s[20:21], 0
	v_readlane_b32 s41, v254, 18
	v_readlane_b32 s42, v254, 19
	v_readlane_b32 s43, v254, 20
	v_readlane_b32 s44, v254, 21
	v_readlane_b32 s45, v254, 22
	v_readlane_b32 s48, v254, 25
	v_readlane_b32 s49, v254, 26
	v_readlane_b32 s50, v254, 27
	v_readlane_b32 s51, v254, 28
	s_branch .Lq_14

.Lq_26:
	s_mov_b32 s0, s101
	s_add_i32 s41, s41, s0
	s_cmpk_gt_i32 s41, 0x111f
	s_cselect_b64 s[18:19], -1, 0
	s_cmpk_lt_i32 s41, 0x1120
	s_cselect_b64 s[0:1], -1, 0
	s_and_b64 s[20:21], s[0:1], exec
	s_cselect_b32 s30, s41, 0
	s_cmpk_gt_i32 s30, 0x2bf
	s_waitcnt vmcnt(3)
	ds_write_b128 v40, v[2:5]
	s_waitcnt vmcnt(2)
	ds_write_b128 v40, v[6:9] offset:4352
	s_waitcnt vmcnt(1)
	ds_write_b128 v40, v[10:13] offset:8704
	s_waitcnt vmcnt(0)
	ds_write_b128 v40, v[14:17] offset:13056
	s_waitcnt lgkmcnt(0)
	s_barrier
	s_cbranch_scc0 .Lq_33
	s_cmpk_gt_u32 s30, 0x41f
	s_cbranch_scc0 .Lq_34
	s_cmpk_gt_u32 s30, 0x61f
	s_cbranch_scc0 .Lq_35
	s_cmpk_gt_u32 s30, 0x81f
	s_cbranch_scc0 .Lq_36
	s_cmpk_gt_u32 s30, 0x91f
	s_cbranch_scc0 .Lq_38
	s_add_i32 s22, s30, 0xfffff6e0
	s_lshr_b32 s4, s22, 8
	v_readlane_b32 s44, v254, 13
	s_lshr_b32 s24, s22, 5
	s_lshl_b64 s[20:21], s[4:5], 22
	v_readlane_b32 s54, v254, 23
	v_readlane_b32 s55, v254, 24
	s_add_u32 s4, s54, s20
	s_addc_u32 s20, s55, s21
	s_lshl_b32 s21, s22, 4
	s_and_b32 s21, s21, 0xe00
	s_add_u32 s22, s4, s21
	v_readlane_b32 s56, v254, 25
	v_readlane_b32 s57, v254, 26
	v_readlane_b32 s58, v254, 27
	v_readlane_b32 s59, v254, 28
	s_addc_u32 s23, s20, 0
	s_mul_hi_u32 s4, s24, 0x44000
	s_mul_i32 s24, s24, 0x44000
	v_readlane_b32 s56, v254, 45
	s_add_u32 s20, s3, s24
	v_readlane_b32 s45, v254, 14
	v_readlane_b32 s46, v254, 15
	v_readlane_b32 s47, v254, 16
	v_readlane_b32 s48, v254, 17
	v_readlane_b32 s49, v254, 18
	v_readlane_b32 s50, v254, 19
	v_readlane_b32 s51, v254, 20
	v_readlane_b32 s52, v254, 21
	v_readlane_b32 s53, v254, 22
	v_readlane_b32 s57, v254, 46
	v_readlane_b32 s58, v254, 47
	v_readlane_b32 s59, v254, 48
	v_readlane_b32 s60, v254, 49
	v_readlane_b32 s61, v254, 50
	v_readlane_b32 s62, v254, 51
	v_readlane_b32 s63, v254, 52
	v_readlane_b32 s64, v254, 53
	v_readlane_b32 s65, v254, 54
	v_readlane_b32 s66, v254, 55
	v_readlane_b32 s67, v254, 56
	v_readlane_b32 s68, v254, 57
	v_readlane_b32 s69, v254, 58
	v_readlane_b32 s70, v254, 59
	v_readlane_b32 s71, v254, 60
	s_addc_u32 s21, s33, s4
	s_bfe_u32 s4, s30, 0x40001
	s_and_b32 s42, s30, 1
	s_cbranch_execz .Lq_39
	s_movk_i32 s44, 0x440
	s_mov_b32 s43, 0
	s_branch .Lq_40

.Lq_64:
	s_mov_b32 s2, s100
	s_mov_b32 s0, s101
	v_lshl_add_u32 v18, s2, 8, v144
	s_lshl_b32 s8, s0, 8
	s_mov_b32 s0, 0x48000
	v_cmp_gt_i32_e32 vcc, s0, v18
	s_and_saveexec_b64 s[0:1], vcc
	s_branch .Lq_69
	s_add_u32 s4, s90, 0x1bdc8000
	s_addc_u32 s5, s91, 0
	s_mov_b64 s[10:11], 0
	s_mov_b32 s3, 0x2aaaaaab
	s_movk_i32 s9, 0xffa0
	s_movk_i32 s14, 0x60
	s_movk_i32 s15, 0x58
	s_mov_b32 s16, 0x38e38e39
	s_mov_b32 s17, 0x47fff
	s_waitcnt vmcnt(3)
	v_mov_b32_e32 v3, 0
	s_movk_i32 s18, 0x160
	v_mov_b32_e32 v4, v18
	s_branch .Lq_67

.Lq_72:
	s_or_b64 exec, exec, s[0:1]
	s_mov_b32 s3, 0x200000
	v_cmp_gt_i32_e32 vcc, s3, v18
	s_and_saveexec_b64 s[10:11], vcc
	s_cbranch_execz .Lq_87
	s_add_u32 s12, s90, 0x18988000
	s_addc_u32 s13, s91, 0
	s_mov_b32 s0, s101
	s_add_i32 s24, s8, s8
	s_ashr_i32 s9, s8, 31
	v_lshl_add_u32 v23, s2, 10, v27
	s_lshl_b32 s18, s0, 12
	s_lshl_b32 s19, s0, 9
	s_lshl_b32 s20, s0, 11
	s_mul_i32 s21, s0, 0x300
	s_mul_i32 s22, s0, 0xc00
	s_lshl_b32 s23, s0, 10
	s_mov_b64 s[14:15], 0
	v_mov_b32_e32 v21, 0
	s_add_i32 s24, s24, s8
	s_mov_b32 s25, 0x1fffff
	v_mov_b32_e32 v24, v18
	s_branch .Lq_75

.Lq_87:
	s_or_b64 exec, exec, s[10:11]
	s_waitcnt vmcnt(3)
	v_cvt_f32_u32_e32 v2, s8
	s_mov_b32 s0, 0x30000
	v_cmp_gt_i32_e32 vcc, s0, v18
	v_add_u32_e32 v3, s8, v18
	s_waitcnt vmcnt(2)
	v_rcp_iflag_f32_e32 v8, v2
	s_and_saveexec_b64 s[4:5], vcc
	s_cbranch_execz .Lq_102
	v_mul_f32_e32 v5, 0x4f7ffffe, v8
	v_cvt_u32_f32_e32 v5, v5
	v_mov_b32_e32 v4, s8
	v_cmp_gt_i32_e32 vcc, s0, v3
	v_max_i32_e32 v2, 0x30000, v3
	s_mov_b64 s[12:13], -1
	v_addc_co_u32_e64 v4, s[0:1], v18, v4, vcc
	s_sub_i32 s0, 0, s8
	v_sub_u32_e32 v2, v2, v4
	v_mul_lo_u32 v4, s0, v5
	v_mul_hi_u32 v4, v5, v4
	v_add_u32_e32 v4, v5, v4
	v_mul_hi_u32 v4, v2, v4
	v_mul_lo_u32 v5, v4, s8
	v_sub_u32_e32 v2, v2, v5
	v_add_u32_e32 v5, 1, v4
	v_cmp_le_u32_e64 s[0:1], s8, v2
	s_nop 1
	v_cndmask_b32_e64 v4, v4, v5, s[0:1]
	v_subrev_u32_e32 v5, s8, v2
	v_cndmask_b32_e64 v2, v2, v5, s[0:1]
	v_add_u32_e32 v5, 1, v4
	v_cmp_le_u32_e64 s[0:1], s8, v2
	s_nop 1
	v_cndmask_b32_e64 v2, v4, v5, s[0:1]
	v_addc_co_u32_e32 v9, vcc, 1, v2, vcc
	v_cmp_lt_u32_e64 s[0:1], 1, v9
	s_waitcnt vmcnt(1)
	v_and_b32_e32 v10, -2, v9
	v_mov_b32_e32 v4, v18
	s_and_saveexec_b64 s[10:11], s[0:1]
	s_cbranch_execz .Lq_92
	s_mov_b32 s3, s101
	v_and_b32_e32 v6, -2, v9
	v_mov_b32_e32 v2, v18
	s_lshl_b32 s3, s3, 9
	s_mov_b32 s9, s3
	s_mov_b64 s[12:13], 0
	s_mov_b32 s14, 0x2aaaaaab
	s_mov_b32 s15, 0x18b90000
	v_mov_b32_e32 v7, 0
	v_mov_b32_e32 v11, v6
	v_mov_b64_e32 v[4:5], v[2:3]
	s_waitcnt vmcnt(0)

.Lq_95:
	s_or_b64 exec, exec, s[10:11]
	s_mov_b64 s[12:13], -1
	v_mov_b32_e32 v4, v18
	s_and_saveexec_b64 s[10:11], s[0:1]
	s_cbranch_execz .Lq_99
	s_mov_b32 s0, s101
	v_mov_b32_e32 v2, v18
	s_lshl_b32 s3, s0, 9
	s_mov_b32 s9, s3
	s_mov_b64 s[0:1], 0
	s_mov_b32 s12, 0x2aaaaaab
	s_movk_i32 s13, 0x880
	v_mov_b64_e32 v[4:5], s[90:91]
	s_mov_b32 s14, 0x19a88000
	v_mov_b32_e32 v11, 0
	v_mov_b32_e32 v12, v10
	v_mov_b64_e32 v[6:7], v[2:3]
	s_waitcnt vmcnt(0)

.Lq_102:
	s_or_b64 exec, exec, s[4:5]
	v_readlane_b32 s56, v254, 45
	v_readlane_b32 s57, v254, 46
	v_readlane_b32 s58, v254, 47
	v_readlane_b32 s59, v254, 48
	v_readlane_b32 s60, v254, 49
	v_readlane_b32 s61, v254, 50
	v_readlane_b32 s62, v254, 51
	v_readlane_b32 s63, v254, 52
	v_readlane_b32 s64, v254, 53
	v_readlane_b32 s65, v254, 54
	v_readlane_b32 s66, v254, 55
	v_readlane_b32 s67, v254, 56
	v_readlane_b32 s68, v254, 57
	v_readlane_b32 s69, v254, 58
	v_readlane_b32 s70, v254, 59
	v_readlane_b32 s71, v254, 60
.Lprep2_skip:
	s_mov_b64 s[0:1], exec
	v_readlane_b32 s2, v254, 11
	v_readlane_b32 s3, v254, 12
	s_and_b64 s[2:3], s[0:1], s[2:3]
	s_mov_b64 exec, s[2:3]
	s_cbranch_execz .LBB0_304
	s_mov_b64 s[2:3], exec
	v_mbcnt_lo_u32_b32 v0, s2, 0
	v_mbcnt_hi_u32_b32 v0, s3, v0
	s_getreg_b32 s6, hwreg(HW_REG_HW_ID)
	s_getreg_b32 s7, hwreg(HW_REG_XCC_ID)
	v_cmp_eq_u32_e32 vcc, 0, v0
	s_and_saveexec_b64 s[4:5], vcc
	s_cbranch_execz .LBB0_303
	s_lshl_b32 s7, s7, 8
	s_and_b32 s7, s7, 0x700
	s_bfe_u32 s6, s6, 0x80008
	s_or_b32 s6, s7, s6
	s_lshl_b32 s6, s6, 2
	s_add_u32 s6, s90, s6
	s_addc_u32 s7, s91, 0
	s_bcnt1_i32_b64 s2, s[2:3]
	v_mov_b32_e32 v1, 0x1bf98000
	v_mov_b32_e32 v2, s2
	global_atomic_add v1, v1, v2, s[6:7] offset:1280 sc0

	.amdhsa_kernel _Z14hawk_yoco_mega6Params
		.amdhsa_group_segment_fixed_size 0
		.amdhsa_private_segment_fixed_size 0
		.amdhsa_kernarg_size 504
		.amdhsa_user_sgpr_count 2
		.amdhsa_user_sgpr_dispatch_ptr 0
		.amdhsa_user_sgpr_queue_ptr 0
		.amdhsa_user_sgpr_kernarg_segment_ptr 1
		.amdhsa_user_sgpr_dispatch_id 0
		.amdhsa_user_sgpr_kernarg_preload_length 0
		.amdhsa_user_sgpr_kernarg_preload_offset 0
		.amdhsa_user_sgpr_private_segment_size 0
		.amdhsa_uses_dynamic_stack 0
		.amdhsa_enable_private_segment 0
		.amdhsa_system_sgpr_workgroup_id_x 1
		.amdhsa_system_sgpr_workgroup_id_y 0
		.amdhsa_system_sgpr_workgroup_id_z 0
		.amdhsa_system_sgpr_workgroup_info 0
		.amdhsa_system_vgpr_workitem_id 2
		.amdhsa_next_free_vgpr 255
		.amdhsa_next_free_sgpr 102
		.amdhsa_accum_offset 256
		.amdhsa_reserve_vcc 1
		.amdhsa_float_round_mode_32 0
		.amdhsa_float_round_mode_16_64 0
		.amdhsa_float_denorm_mode_32 3
		.amdhsa_float_denorm_mode_16_64 3
		.amdhsa_dx10_clamp 1
		.amdhsa_ieee_mode 1
		.amdhsa_fp16_overflow 0
		.amdhsa_tg_split 0
		.amdhsa_exception_fp_ieee_invalid_op 0
		.amdhsa_exception_fp_denorm_src 0
		.amdhsa_exception_fp_ieee_div_zero 0
		.amdhsa_exception_fp_ieee_overflow 0
		.amdhsa_exception_fp_ieee_underflow 0
		.amdhsa_exception_fp_ieee_inexact 0
		.amdhsa_exception_int_div_zero 0
	.end_amdhsa_kernel

amdhsa.kernels:
  - .agpr_count:     0
    .args:
      - .offset:         0
        .size:           248
        .value_kind:     by_value
      - .offset:         248
        .size:           4
        .value_kind:     hidden_block_count_x
      - .offset:         252
        .size:           4
        .value_kind:     hidden_block_count_y
      - .offset:         256
        .size:           4
        .value_kind:     hidden_block_count_z
      - .offset:         260
        .size:           2
        .value_kind:     hidden_group_size_x
      - .offset:         262
        .size:           2
        .value_kind:     hidden_group_size_y
      - .offset:         264
        .size:           2
        .value_kind:     hidden_group_size_z
      - .offset:         266
        .size:           2
        .value_kind:     hidden_remainder_x
      - .offset:         268
        .size:           2
        .value_kind:     hidden_remainder_y
      - .offset:         270
        .size:           2
        .value_kind:     hidden_remainder_z
      - .offset:         288
        .size:           8
        .value_kind:     hidden_global_offset_x
      - .offset:         296
        .size:           8
        .value_kind:     hidden_global_offset_y
      - .offset:         304
        .size:           8
        .value_kind:     hidden_global_offset_z
      - .offset:         312
        .size:           2
        .value_kind:     hidden_grid_dims
      - .offset:         336
        .size:           8
        .value_kind:     hidden_multigrid_sync_arg
      - .offset:         368
        .size:           4
        .value_kind:     hidden_dynamic_lds_size
    .group_segment_fixed_size: 0
    .kernarg_segment_align: 8
    .kernarg_segment_size: 504
    .language:       OpenCL C
    .language_version:
      - 2
      - 0
    .max_flat_workgroup_size: 256
    .name:           _Z14hawk_yoco_mega6Params
    .private_segment_fixed_size: 0
    .sgpr_count:     108
    .sgpr_spill_count: 71
    .symbol:         _Z14hawk_yoco_mega6Params.kd
    .uniform_work_group_size: 1
    .uses_dynamic_stack: false
    .vgpr_count:     255
    .vgpr_spill_count: 0
    .wavefront_size: 64
